# attention: s_setprio 1 around every MFMA run (matrix-pipe issue preferred over the partner wave's softmax VALU)
# speedup vs baseline: 1.0350x; 1.0015x over previous
; #define QF(d0, jj) __uint_as_float(((unsigned)(unsigned short)qr[d0][jj]) << 16)
; template <typename TQ>
; __device__ __forceinline__ void attn_dense_body(const TQ* __restrict__ Qb, const bf16* __restrict__ Kh, const bf16* __restrict__ Vh,
;                                                 unsigned short* __restrict__ Ob, int seq, char* lds, const float* __restrict__ qg, int pos0) {
;     ...
;   int tid_ = threadIdx.x; asm volatile("" : "+v"(tid_));
;   const int tid = tid_, wid = tid >> 6, lane = tid & 63, r32 = lane & 31, hi = lane >> 5;
;   bf16* V_lds = (bf16*)lds; bf16* K_lds = (bf16*)(lds + 2 * SHM_V);
;   float* ws = (float*)(lds + 2 * SHM_V + 2 * SHM_K) + wid * 64; float* li_l = ws; float* al_l = ws + 32;
;   float m_reg = -1e30f, l_reg = 0; f32x16 o[4] = {}; bf16x8 qr[8];
;   const TQ* Qw = Qb + (long)(wid * QBLK + r32) * LDQ + hi * 8;
; #pragma unroll
;   for (int d0 = 0; d0 < 8; ++d0) qr[d0] = SQ::tobf(SQ::ld8(Qw + d0 * 16));
;   {
;     ...
;     int hi2 = hi; asm volatile("" : "+v"(hi2));
;     const float* qg2 = qg; asm volatile("" : "+s"(qg2));
;     float ss = 0.f;
; #pragma unroll
;     for (int d0 = 0; d0 < 8; ++d0)
; #pragma unroll
;       for (int jj = 0; jj < 8; ++jj) { const float x = QF(d0, jj); ss += x * x; }
;     ss += __shfl_xor(ss, 32);
;     const float ri = rsqrtf(ss * (1.0f / 128.0f) + 1e-6f);
; __device__ __forceinline__ void attn_phase(unsigned char* lds, const bf16_t* Z2, bf16_t* OA, const float* __restrict__ qg, int bi, int nb, int nunits) {
;     ...
;         if (nunits == 512 && nb == 128) { const int x = bi & 3, t = i_ * 32 + (bi >> 2), bk = x * 4 + (t >> 5);
;             u = ((bk >> 1) << 6) | ((((bk & 1) << 2) | ((t >> 3) & 3)) << 3) | (t & 7); }
;         const int qb = u & 7, hq = (u >> 3) & 7, b = u >> 6, kvh = hq >> 2;
;         const size_t row0 = (size_t)b * SEQ;
;         const attn::bf16* Qb = (const attn::bf16*)(Z2 + (row0 + qb * 256) * NZ2 + hq * 128);
;         const attn::bf16* Kh = (const attn::bf16*)(Z2 + row0 * NZ2 + 1024 + kvh * 128);
;         const attn::bf16* Vh = (const attn::bf16*)(Z2 + row0 * NZ2 + 1280 + kvh * 128);
;         attn::attn_dense_body<attn::bf16>(Qb, Kh, Vh, OA + (row0 + qb * 256) * DM + hq * 128, SEQ, (char*)lds, qg, qb * 256);
.LBB0_904:
	s_ashr_i32 s6, s9, 6
	s_ashr_i32 s7, s6, 31
	s_lshl_b32 s5, s9, 8
	s_lshl_b64 s[28:29], s[6:7], 11
	s_and_b32 s7, s5, 0x700
	s_or_b32 s28, s28, s7
	s_mul_i32 s5, s29, 0x1c00
	s_mul_hi_u32 s10, s28, 0x1c00
	s_bfe_u32 s4, s9, 0x30003
	s_add_i32 s10, s10, s5
	s_mul_i32 s5, s28, 0x1c00
	s_add_u32 s5, s34, s5
	s_addc_u32 s10, s35, s10
	s_lshl_b32 s57, s4, 7
	s_lshl_b32 s4, s4, 8
	s_add_u32 s4, s5, s4
	v_mov_b32_e32 v74, v181
	s_addc_u32 s5, s10, 0
	v_mov_b64_e32 v[0:1], s[4:5]
	v_ashrrev_i32_e32 v45, 1, v74
	v_bfe_u32 v196, v74, 5, 1
	v_bfi_b32 v2, s41, v45, v74
	v_mad_i64_i32 v[0:1], s[4:5], v2, s39, v[0:1]
	v_lshlrev_b32_e32 v182, 4, v196
	v_lshl_add_u64 v[4:5], v[0:1], 0, v[182:183]
	global_load_dwordx4 v[28:31], v[4:5], off
	global_load_dwordx4 v[24:27], v[4:5], off offset:32
	global_load_dwordx4 v[20:23], v[4:5], off offset:64
	global_load_dwordx4 v[16:19], v[4:5], off offset:96
	global_load_dwordx4 v[12:15], v[4:5], off offset:128
	global_load_dwordx4 v[8:11], v[4:5], off offset:160
	global_load_dwordx4 v[0:3], v[4:5], off offset:192
	v_mov_b32_e32 v32, v196
	global_load_dwordx4 v[4:7], v[4:5], off offset:224
	v_readlane_b32 s60, v245, 0
	v_readlane_b32 s70, v245, 10
	v_readlane_b32 s71, v245, 11
	v_lshlrev_b32_e32 v32, 3, v32
	s_mov_b64 s[4:5], s[70:71]
	v_ashrrev_i32_e32 v33, 31, v32
	v_cmp_lt_i32_e32 vcc, v194, v195
	v_lshl_add_u64 v[34:35], v[32:33], 2, s[4:5]
	flat_load_dwordx2 v[76:77], v[34:35]
	flat_load_dwordx2 v[78:79], v[34:35] offset:128
	flat_load_dwordx2 v[88:89], v[34:35] offset:256
	flat_load_dwordx2 v[90:91], v[34:35] offset:384
	v_and_b32_e32 v197, 31, v74
	v_and_b32_e32 v184, 0xffffffe0, v45
	s_mul_i32 s5, s6, 0xe00000
	s_mul_hi_i32 s4, s6, 0xe00000
	s_add_u32 s5, s34, s5
	s_addc_u32 s10, s35, s4
	s_lshl_b32 s4, s9, 3
	s_mov_b32 s9, s8
	s_mov_b32 s12, s8
	s_mov_b32 s13, s8
	s_mov_b32 s14, s8
	s_mov_b32 s15, s8
	s_mov_b32 s16, s8
	s_mov_b32 s17, s8
	s_mov_b32 s18, s8
	s_mov_b32 s19, s8
	s_mov_b32 s20, s8
	s_mov_b32 s21, s8
	s_mov_b32 s22, s8
	s_mov_b32 s23, s8
	v_readlane_b32 s72, v245, 12
	v_readlane_b32 s73, v245, 13
	s_mov_b32 s58, -1
	v_mov_b32_e32 v199, 0
	s_mov_b64 s[72:73], s[80:81]
	v_readlane_b32 s61, v245, 1
	v_readlane_b32 s62, v245, 2
	v_readlane_b32 s63, v245, 3
	v_readlane_b32 s64, v245, 4
	v_readlane_b32 s65, v245, 5
	v_readlane_b32 s66, v245, 6
	v_readlane_b32 s67, v245, 7
	v_readlane_b32 s68, v245, 8
	v_readlane_b32 s69, v245, 9
	v_readlane_b32 s74, v245, 14
	v_readlane_b32 s75, v245, 15
	s_waitcnt vmcnt(0)
	v_and_b32_e32 v82, 0xffff0000, v28
	v_lshlrev_b32_e32 v80, 16, v28
	v_lshlrev_b32_e32 v70, 16, v29
	v_and_b32_e32 v66, 0xffff0000, v29
	v_lshlrev_b32_e32 v52, 16, v31
	v_and_b32_e32 v48, 0xffff0000, v31
	v_lshlrev_b32_e32 v43, 16, v16
	v_and_b32_e32 v41, 0xffff0000, v16
	v_lshlrev_b32_e32 v31, 16, v18
	v_and_b32_e32 v29, 0xffff0000, v18
	v_lshlrev_b32_e32 v18, 16, v9
	v_and_b32_e32 v16, 0xffff0000, v9
	v_mul_f32_e32 v9, v82, v82
	v_fmac_f32_e32 v9, v80, v80
	v_fmac_f32_e32 v9, v70, v70
	v_lshlrev_b32_e32 v62, 16, v30
	v_fmac_f32_e32 v9, v66, v66
	v_and_b32_e32 v58, 0xffff0000, v30
	v_fmac_f32_e32 v9, v62, v62
	v_fmac_f32_e32 v9, v58, v58
	v_fmac_f32_e32 v9, v52, v52
	v_lshlrev_b32_e32 v42, 16, v24
	v_fmac_f32_e32 v9, v48, v48
	v_and_b32_e32 v40, 0xffff0000, v24
	v_fmac_f32_e32 v9, v42, v42
	v_lshlrev_b32_e32 v38, 16, v25
	v_fmac_f32_e32 v9, v40, v40
	v_and_b32_e32 v36, 0xffff0000, v25
	v_fmac_f32_e32 v9, v38, v38
	v_lshlrev_b32_e32 v30, 16, v26
	v_fmac_f32_e32 v9, v36, v36
	v_and_b32_e32 v28, 0xffff0000, v26
	v_fmac_f32_e32 v9, v30, v30
	v_lshlrev_b32_e32 v26, 16, v27
	v_fmac_f32_e32 v9, v28, v28
	v_and_b32_e32 v24, 0xffff0000, v27
	v_fmac_f32_e32 v9, v26, v26
	v_lshlrev_b32_e32 v81, 16, v20
	v_fmac_f32_e32 v9, v24, v24
	v_and_b32_e32 v83, 0xffff0000, v20
	v_fmac_f32_e32 v9, v81, v81
	v_lshlrev_b32_e32 v71, 16, v21
	v_fmac_f32_e32 v9, v83, v83
	v_and_b32_e32 v67, 0xffff0000, v21
	v_fmac_f32_e32 v9, v71, v71
	v_lshlrev_b32_e32 v63, 16, v22
	v_fmac_f32_e32 v9, v67, v67
	v_and_b32_e32 v59, 0xffff0000, v22
	v_fmac_f32_e32 v9, v63, v63
	v_lshlrev_b32_e32 v53, 16, v23
	v_fmac_f32_e32 v9, v59, v59
	v_and_b32_e32 v49, 0xffff0000, v23
	v_fmac_f32_e32 v9, v53, v53
	v_fmac_f32_e32 v9, v49, v49
	v_fmac_f32_e32 v9, v43, v43
	v_lshlrev_b32_e32 v39, 16, v17
	v_fmac_f32_e32 v9, v41, v41
	v_and_b32_e32 v37, 0xffff0000, v17
	v_fmac_f32_e32 v9, v39, v39
	v_fmac_f32_e32 v9, v37, v37
	v_fmac_f32_e32 v9, v31, v31
	v_lshlrev_b32_e32 v27, 16, v19
	v_fmac_f32_e32 v9, v29, v29
	v_and_b32_e32 v25, 0xffff0000, v19
	v_fmac_f32_e32 v9, v27, v27
	v_lshlrev_b32_e32 v84, 16, v12
	v_fmac_f32_e32 v9, v25, v25
	v_and_b32_e32 v86, 0xffff0000, v12
	v_fmac_f32_e32 v9, v84, v84
	v_lshlrev_b32_e32 v72, 16, v13
	v_fmac_f32_e32 v9, v86, v86
	v_and_b32_e32 v68, 0xffff0000, v13
	v_fmac_f32_e32 v9, v72, v72
	v_lshlrev_b32_e32 v64, 16, v14
	v_fmac_f32_e32 v9, v68, v68
	v_and_b32_e32 v60, 0xffff0000, v14
	v_fmac_f32_e32 v9, v64, v64
	v_lshlrev_b32_e32 v54, 16, v15
	v_fmac_f32_e32 v9, v60, v60
	v_and_b32_e32 v50, 0xffff0000, v15
	v_fmac_f32_e32 v9, v54, v54
	v_lshlrev_b32_e32 v44, 16, v8
	v_fmac_f32_e32 v9, v50, v50
	v_and_b32_e32 v22, 0xffff0000, v8
	v_fmac_f32_e32 v9, v44, v44
	v_fmac_f32_e32 v9, v22, v22
	v_fmac_f32_e32 v9, v18, v18
	v_lshlrev_b32_e32 v14, 16, v10
	v_fmac_f32_e32 v9, v16, v16
	v_and_b32_e32 v12, 0xffff0000, v10
	v_fmac_f32_e32 v9, v14, v14
	v_lshlrev_b32_e32 v10, 16, v11
	v_fmac_f32_e32 v9, v12, v12
	v_and_b32_e32 v8, 0xffff0000, v11
	v_fmac_f32_e32 v9, v10, v10
	v_lshlrev_b32_e32 v85, 16, v0
	v_fmac_f32_e32 v9, v8, v8
	v_and_b32_e32 v87, 0xffff0000, v0
	v_fmac_f32_e32 v9, v85, v85
	v_fmac_f32_e32 v9, v87, v87
	v_lshlrev_b32_e32 v73, 16, v1
	v_fmac_f32_e32 v9, v73, v73
	v_and_b32_e32 v69, 0xffff0000, v1
	v_fmac_f32_e32 v9, v69, v69
	v_lshlrev_b32_e32 v65, 16, v2
	v_fmac_f32_e32 v9, v65, v65
	v_and_b32_e32 v61, 0xffff0000, v2
	v_and_b32_e32 v57, 0xffff0000, v3
	v_lshlrev_b32_e32 v56, 16, v3
	v_fmac_f32_e32 v9, v61, v61
	v_pk_mul_f32 v[0:1], v[56:57], v[56:57]
	v_and_b32_e32 v47, 0xffff0000, v4
	v_add_f32_e32 v0, v0, v9
	v_lshlrev_b32_e32 v46, 16, v4
	v_add_f32_e32 v2, v1, v0
	v_pk_mul_f32 v[0:1], v[46:47], v[46:47]
	v_and_b32_e32 v21, 0xffff0000, v5
	v_add_f32_e32 v0, v0, v2
	v_lshlrev_b32_e32 v20, 16, v5
	v_add_f32_e32 v2, v1, v0
	v_pk_mul_f32 v[0:1], v[20:21], v[20:21]
	v_and_b32_e32 v5, 0xffff0000, v6
	v_add_f32_e32 v0, v0, v2
	v_lshlrev_b32_e32 v4, 16, v6
	v_add_f32_e32 v2, v1, v0
	v_pk_mul_f32 v[0:1], v[4:5], v[4:5]
	v_or_b32_e32 v11, 1, v32
	v_add_f32_e32 v0, v0, v2
	v_add_f32_e32 v6, v1, v0
	v_and_b32_e32 v1, 0xffff0000, v7
	v_lshlrev_b32_e32 v0, 16, v7
	v_pk_mul_f32 v[2:3], v[0:1], v[0:1]
	v_cvt_f32_i32_e32 v7, v32
	v_add_f32_e32 v2, v2, v6
	v_add_f32_e32 v2, v3, v2
	v_cndmask_b32_e32 v3, v193, v194, vcc
	v_lshlrev_b32_e32 v3, 2, v3
	ds_bpermute_b32 v3, v3, v2
	v_or_b32_e32 v6, s7, v197
	v_add_u32_e32 v6, v6, v184
	v_ashrrev_i32_e32 v9, 6, v6
	v_cvt_f32_i32_e32 v11, v11
	s_waitcnt lgkmcnt(0)
; #define QW(d0) (u ? __uint_as_float(qv[d0][jp] & 0xffff0000u) : __uint_as_float(qv[d0][jp] << 16))
; template <typename TQ>
; __device__ __forceinline__ void attn_dense_body(const TQ* __restrict__ Qb, const bf16* __restrict__ Kh, const bf16* __restrict__ Vh,
;                                                 unsigned short* __restrict__ Ob, int seq, char* lds, const float* __restrict__ qg, int pos0) {
;     ...
;     const float ri = rsqrtf(ss * (1.0f / 128.0f) + 1e-6f);
;     const int pos = pos0 + wid * QBLK + r32; const float prow = (float)(pos >> 6), pcol = (float)(pos & 63);
;     u32x4 qv[8];
; #pragma unroll
;     for (int d0 = 0; d0 < 8; ++d0) qv[d0] = *reinterpret_cast<u32x4*>(&qr[d0]);
; #pragma unroll
;     for (int dd = 0; dd < 2; ++dd)
; #pragma unroll
;       for (int jp = 0; jp < 4; ++jp) { float o[4][2];
; #pragma unroll
;         for (int u = 0; u < 2; ++u) { const int jj = 2 * jp + u, e0 = 16 * dd + 8 * hi2 + jj;
;           const float invf = exp2f(-(float)e0 * (13.287712379549449f / 32.0f));
;           const float ar = prow * invf, ac = pcol * invf;
;           const float sr_ = __sinf(ar), cr_ = __cosf(ar), sc_ = __sinf(ac), cc_ = __cosf(ac);
;     ...
;           const float a1 = QW(dd) * ri * qg2[e0], a2 = QW(dd + 2) * ri * qg2[32 + e0], b1 = QW(4 + dd) * ri * qg2[64 + e0], b2 = QW(6 + dd) * ri * qg2[96 + e0];
;     ...
;           o[0][u] = a1 * cr_ - a2 * sr_; o[1][u] = a2 * cr_ + a1 * sr_; o[2][u] = b1 * cc_ - b2 * sc_; o[3][u] = b2 * cc_ + b1 * sc_; }
;         qv[dd][jp] = cvtpk(o[0][0], o[0][1]); qv[dd + 2][jp] = cvtpk(o[1][0], o[1][1]); qv[4 + dd][jp] = cvtpk(o[2][0], o[2][1]); qv[6 + dd][jp] = cvtpk(o[3][0], o[3][1]); }
	v_add_f32_e32 v2, v2, v3
	v_fmamk_f32 v2, v2, 0x3c000000, v179
	v_mul_f32_e32 v3, 0x4b800000, v2
	v_cmp_gt_f32_e32 vcc, s42, v2
	v_and_b32_e32 v6, 63, v6
	v_mul_f32_e32 v15, 0xbed49a78, v11
	v_cndmask_b32_e32 v2, v2, v3, vcc
	v_rsq_f32_e32 v2, v2
	v_cvt_f32_ubyte0_e32 v6, v6
	v_mov_b32_e32 v96, v76
	v_mov_b32_e32 v97, v78
	v_mul_f32_e32 v3, 0x45800000, v2
	v_cndmask_b32_e32 v2, v2, v3, vcc
	v_mul_f32_e32 v3, 0xbed49a78, v7
	v_cmp_gt_f32_e32 vcc, s43, v3
	v_mov_b32_e32 v78, v77
	v_mov_b32_e32 v55, v56
	v_cndmask_b32_e32 v3, 0, v189, vcc
	v_fmac_f32_e32 v3, 0xbed49a78, v7
	v_exp_f32_e32 v7, v3
	v_cvt_f32_i32_e32 v3, v9
	v_cndmask_b32_e32 v9, 0, v190, vcc
	v_cmp_gt_f32_e32 vcc, s43, v15
	v_ldexp_f32 v7, v7, v9
	v_mul_f32_e32 v9, v7, v3
	v_mul_f32_e32 v9, 0.15915494, v9
	v_sin_f32_e32 v93, v9
	v_cos_f32_e32 v92, v9
	v_pk_mul_f32 v[80:81], v[2:3], v[80:81] op_sel_hi:[0,1]
	v_mul_f32_e32 v7, v7, v6
	v_pk_mul_f32 v[80:81], v[96:97], v[80:81]
	v_cndmask_b32_e32 v15, 0, v189, vcc
	v_mul_f32_e32 v7, 0.15915494, v7
	v_pk_mul_f32 v[96:97], v[92:93], v[80:81]
	v_fmac_f32_e32 v15, 0xbed49a78, v11
	v_sin_f32_e32 v95, v7
	v_cos_f32_e32 v94, v7
	v_sub_f32_e32 v7, v96, v97
	v_mov_b32_e32 v96, v93
	v_mov_b32_e32 v97, v92
	v_exp_f32_e32 v11, v15
	v_pk_mul_f32 v[80:81], v[96:97], v[80:81]
	v_cndmask_b32_e32 v17, 0, v190, vcc
	v_add_f32_e32 v9, v80, v81
	v_pk_mul_f32 v[80:81], v[2:3], v[84:85] op_sel_hi:[0,1]
	v_mov_b32_e32 v84, v88
	v_mov_b32_e32 v85, v90
	v_pk_mul_f32 v[80:81], v[84:85], v[80:81]
	v_ldexp_f32 v11, v11, v17
	v_pk_mul_f32 v[84:85], v[94:95], v[80:81]
	v_mul_f32_e32 v17, v11, v3
	v_sub_f32_e32 v13, v84, v85
	v_mov_b32_e32 v84, v95
	v_mov_b32_e32 v85, v94
	v_pk_mul_f32 v[80:81], v[84:85], v[80:81]
	v_mul_f32_e32 v17, 0.15915494, v17
	v_add_f32_e32 v15, v80, v81
	v_sin_f32_e32 v81, v17
	v_cos_f32_e32 v80, v17
	v_pk_mul_f32 v[82:83], v[2:3], v[82:83] op_sel_hi:[0,1]
	v_mul_f32_e32 v11, v11, v6
	v_pk_mul_f32 v[76:77], v[78:79], v[82:83]
	v_mul_f32_e32 v11, 0.15915494, v11
	v_pk_mul_f32 v[78:79], v[80:81], v[76:77]
	v_sin_f32_e32 v85, v11
	v_cos_f32_e32 v84, v11
	v_sub_f32_e32 v11, v78, v79
	v_mov_b32_e32 v78, v81
	v_mov_b32_e32 v79, v80
	v_pk_mul_f32 v[76:77], v[78:79], v[76:77]
	v_mov_b32_e32 v90, v89
	v_add_f32_e32 v17, v76, v77
	v_pk_mul_f32 v[76:77], v[2:3], v[86:87] op_sel_hi:[0,1]
	v_pk_mul_f32 v[76:77], v[90:91], v[76:77]
	v_cvt_pk_bf16_f32 v108, v7, v11
	v_cvt_pk_bf16_f32 v104, v9, v17
	v_or_b32_e32 v7, 2, v32
	v_pk_mul_f32 v[78:79], v[84:85], v[76:77]
	v_cvt_f32_i32_e32 v7, v7
	v_sub_f32_e32 v19, v78, v79
	v_mov_b32_e32 v78, v85
	v_mov_b32_e32 v79, v84
	v_pk_mul_f32 v[76:77], v[78:79], v[76:77]
	v_cvt_pk_bf16_f32 v100, v13, v19
	v_mul_f32_e32 v9, 0xbed49a78, v7
	v_add_f32_e32 v23, v76, v77
	v_cvt_pk_bf16_f32 v96, v15, v23
	flat_load_dwordx2 v[76:77], v[34:35] offset:8
	flat_load_dwordx2 v[78:79], v[34:35] offset:136
	flat_load_dwordx2 v[80:81], v[34:35] offset:264
	flat_load_dwordx2 v[82:83], v[34:35] offset:392
	v_cmp_gt_f32_e32 vcc, s43, v9
	v_or_b32_e32 v11, 3, v32
	v_cvt_f32_i32_e32 v11, v11
	v_cndmask_b32_e32 v9, 0, v189, vcc
	v_fmac_f32_e32 v9, 0xbed49a78, v7
	v_exp_f32_e32 v7, v9
	v_cndmask_b32_e32 v9, 0, v190, vcc
	v_mul_f32_e32 v15, 0xbed49a78, v11
	v_pk_mul_f32 v[70:71], v[2:3], v[70:71] op_sel_hi:[0,1]
	v_ldexp_f32 v7, v7, v9
	v_mul_f32_e32 v9, v7, v3
	v_mul_f32_e32 v9, 0.15915494, v9
	v_sin_f32_e32 v85, v9
	v_cos_f32_e32 v84, v9
	v_cmp_gt_f32_e32 vcc, s43, v15
	v_mul_f32_e32 v7, v7, v6
	v_mul_f32_e32 v7, 0.15915494, v7
	v_cndmask_b32_e32 v15, 0, v189, vcc
	v_fmac_f32_e32 v15, 0xbed49a78, v11
	v_sin_f32_e32 v87, v7
	v_cos_f32_e32 v86, v7
	v_exp_f32_e32 v11, v15
	v_cndmask_b32_e32 v17, 0, v190, vcc
	v_pk_mul_f32 v[66:67], v[2:3], v[66:67] op_sel_hi:[0,1]
	v_pk_mul_f32 v[62:63], v[2:3], v[62:63] op_sel_hi:[0,1]
	v_ldexp_f32 v11, v11, v17
	v_mul_f32_e32 v17, v11, v3
	v_mul_f32_e32 v17, 0.15915494, v17
	v_mul_f32_e32 v11, v11, v6
	v_mul_f32_e32 v11, 0.15915494, v11
	v_pk_mul_f32 v[58:59], v[2:3], v[58:59] op_sel_hi:[0,1]
	v_pk_mul_f32 v[52:53], v[2:3], v[52:53] op_sel_hi:[0,1]
	v_pk_mul_f32 v[48:49], v[2:3], v[48:49] op_sel_hi:[0,1]
	v_mov_b32_e32 v51, v57
	v_pk_mul_f32 v[42:43], v[2:3], v[42:43] op_sel_hi:[0,1]
	v_mov_b32_e32 v45, v46
	v_pk_mul_f32 v[40:41], v[2:3], v[40:41] op_sel_hi:[0,1]
	v_pk_mul_f32 v[38:39], v[2:3], v[38:39] op_sel_hi:[0,1]
	v_pk_mul_f32 v[36:37], v[2:3], v[36:37] op_sel_hi:[0,1]
	v_pk_mul_f32 v[30:31], v[2:3], v[30:31] op_sel_hi:[0,1]
	v_pk_mul_f32 v[28:29], v[2:3], v[28:29] op_sel_hi:[0,1]
	s_and_b32 s7, s4, 0x100
	s_add_u32 s4, s5, s7
	s_addc_u32 s5, s10, 0
	s_cmp_lg_u32 0, -1
	s_cselect_b32 s59, 0, 0
	s_waitcnt vmcnt(0) lgkmcnt(0)
; #define QW(d0) (u ? __uint_as_float(qv[d0][jp] & 0xffff0000u) : __uint_as_float(qv[d0][jp] << 16))
; template <typename TQ>
; __device__ __forceinline__ void attn_dense_body(const TQ* __restrict__ Qb, const bf16* __restrict__ Kh, const bf16* __restrict__ Vh,
;                                                 unsigned short* __restrict__ Ob, int seq, char* lds, const float* __restrict__ qg, int pos0) {
;     ...
;       for (int jp = 0; jp < 4; ++jp) { float o[4][2];
; #pragma unroll
;         for (int u = 0; u < 2; ++u) { const int jj = 2 * jp + u, e0 = 16 * dd + 8 * hi2 + jj;
;           const float invf = exp2f(-(float)e0 * (13.287712379549449f / 32.0f));
;           const float ar = prow * invf, ac = pcol * invf;
;           const float sr_ = __sinf(ar), cr_ = __cosf(ar), sc_ = __sinf(ac), cc_ = __cosf(ac);
;     ...
;           const float a1 = QW(dd) * ri * qg2[e0], a2 = QW(dd + 2) * ri * qg2[32 + e0], b1 = QW(4 + dd) * ri * qg2[64 + e0], b2 = QW(6 + dd) * ri * qg2[96 + e0];
;     ...
;           o[0][u] = a1 * cr_ - a2 * sr_; o[1][u] = a2 * cr_ + a1 * sr_; o[2][u] = b1 * cc_ - b2 * sc_; o[3][u] = b2 * cc_ + b1 * sc_; }
;         qv[dd][jp] = cvtpk(o[0][0], o[0][1]); qv[dd + 2][jp] = cvtpk(o[1][0], o[1][1]); qv[4 + dd][jp] = cvtpk(o[2][0], o[2][1]); qv[6 + dd][jp] = cvtpk(o[3][0], o[3][1]); }
	v_mov_b32_e32 v88, v76
	v_mov_b32_e32 v89, v78
	v_pk_mul_f32 v[70:71], v[88:89], v[70:71]
	v_mov_b32_e32 v78, v77
	v_pk_mul_f32 v[88:89], v[84:85], v[70:71]
	v_pk_mul_f32 v[66:67], v[78:79], v[66:67]
	v_sub_f32_e32 v7, v88, v89
	v_mov_b32_e32 v88, v85
	v_mov_b32_e32 v89, v84
	v_pk_mul_f32 v[70:71], v[88:89], v[70:71]
	s_nop 0
	v_add_f32_e32 v9, v70, v71
	v_pk_mul_f32 v[70:71], v[2:3], v[72:73] op_sel_hi:[0,1]
	v_mov_b32_e32 v72, v80
	v_mov_b32_e32 v73, v82
	v_pk_mul_f32 v[70:71], v[72:73], v[70:71]
	v_mov_b32_e32 v82, v81
	v_pk_mul_f32 v[72:73], v[86:87], v[70:71]
	s_nop 0
	v_sub_f32_e32 v13, v72, v73
	v_mov_b32_e32 v72, v87
	v_mov_b32_e32 v73, v86
	v_pk_mul_f32 v[70:71], v[72:73], v[70:71]
	v_sin_f32_e32 v73, v11
	v_add_f32_e32 v15, v70, v71
	v_sin_f32_e32 v71, v17
	v_cos_f32_e32 v70, v17
	v_cos_f32_e32 v72, v11
	v_pk_mul_f32 v[76:77], v[70:71], v[66:67]
	s_nop 0
	v_sub_f32_e32 v11, v76, v77
	v_mov_b32_e32 v76, v71
	v_mov_b32_e32 v77, v70
	v_pk_mul_f32 v[66:67], v[76:77], v[66:67]
	v_cvt_pk_bf16_f32 v109, v7, v11
	v_or_b32_e32 v7, 4, v32
	v_add_f32_e32 v17, v66, v67
	v_pk_mul_f32 v[66:67], v[2:3], v[68:69] op_sel_hi:[0,1]
	v_pk_mul_f32 v[66:67], v[82:83], v[66:67]
	v_cvt_pk_bf16_f32 v105, v9, v17
	v_cvt_f32_i32_e32 v7, v7
	v_pk_mul_f32 v[68:69], v[72:73], v[66:67]
	v_or_b32_e32 v11, 5, v32
	v_sub_f32_e32 v19, v68, v69
	v_mov_b32_e32 v68, v73
	v_mov_b32_e32 v69, v72
	v_pk_mul_f32 v[66:67], v[68:69], v[66:67]
	v_cvt_pk_bf16_f32 v101, v13, v19
	v_mul_f32_e32 v9, 0xbed49a78, v7
	v_add_f32_e32 v23, v66, v67
	v_cvt_pk_bf16_f32 v97, v15, v23
	flat_load_dwordx2 v[66:67], v[34:35] offset:16
	flat_load_dwordx2 v[68:69], v[34:35] offset:144
	flat_load_dwordx2 v[70:71], v[34:35] offset:272
	flat_load_dwordx2 v[72:73], v[34:35] offset:400
	v_cmp_gt_f32_e32 vcc, s43, v9
	v_cvt_f32_i32_e32 v11, v11
	v_mul_f32_e32 v15, 0xbed49a78, v11
	v_cndmask_b32_e32 v9, 0, v189, vcc
	v_fmac_f32_e32 v9, 0xbed49a78, v7
	v_exp_f32_e32 v7, v9
	v_cndmask_b32_e32 v9, 0, v190, vcc
	v_cmp_gt_f32_e32 vcc, s43, v15
	v_ldexp_f32 v7, v7, v9
	v_mul_f32_e32 v9, v7, v3
	v_mul_f32_e32 v9, 0.15915494, v9
	v_sin_f32_e32 v77, v9
	v_cos_f32_e32 v76, v9
	v_mul_f32_e32 v7, v7, v6
	v_cndmask_b32_e32 v15, 0, v189, vcc
	v_mul_f32_e32 v7, 0.15915494, v7
	v_fmac_f32_e32 v15, 0xbed49a78, v11
	v_sin_f32_e32 v79, v7
	v_cos_f32_e32 v78, v7
	v_exp_f32_e32 v11, v15
	v_cndmask_b32_e32 v17, 0, v190, vcc
	v_ldexp_f32 v11, v11, v17
	v_mul_f32_e32 v17, v11, v3
	v_mul_f32_e32 v17, 0.15915494, v17
	v_mul_f32_e32 v11, v11, v6
	v_mul_f32_e32 v11, 0.15915494, v11
	s_waitcnt vmcnt(0) lgkmcnt(0)
	v_mov_b32_e32 v80, v66
	v_mov_b32_e32 v81, v68
	v_pk_mul_f32 v[62:63], v[80:81], v[62:63]
	v_mov_b32_e32 v68, v67
	v_pk_mul_f32 v[80:81], v[76:77], v[62:63]
	v_pk_mul_f32 v[58:59], v[68:69], v[58:59]
	v_sub_f32_e32 v7, v80, v81
	v_mov_b32_e32 v80, v77
	v_mov_b32_e32 v81, v76
	v_pk_mul_f32 v[62:63], v[80:81], v[62:63]
	s_nop 0
	v_add_f32_e32 v9, v62, v63
	v_pk_mul_f32 v[62:63], v[2:3], v[64:65] op_sel_hi:[0,1]
	v_mov_b32_e32 v64, v70
	v_mov_b32_e32 v65, v72
	v_pk_mul_f32 v[62:63], v[64:65], v[62:63]
	v_mov_b32_e32 v72, v71
	v_pk_mul_f32 v[64:65], v[78:79], v[62:63]
	s_nop 0
	v_sub_f32_e32 v13, v64, v65
	v_mov_b32_e32 v64, v79
	v_mov_b32_e32 v65, v78
	v_pk_mul_f32 v[62:63], v[64:65], v[62:63]
	v_sin_f32_e32 v65, v11
	v_add_f32_e32 v15, v62, v63
	v_sin_f32_e32 v63, v17
	v_cos_f32_e32 v62, v17
	v_cos_f32_e32 v64, v11
	v_pk_mul_f32 v[66:67], v[62:63], v[58:59]
	s_nop 0
	v_sub_f32_e32 v11, v66, v67
	v_mov_b32_e32 v66, v63
	v_mov_b32_e32 v67, v62
	v_pk_mul_f32 v[58:59], v[66:67], v[58:59]
	v_cvt_pk_bf16_f32 v110, v7, v11
	v_or_b32_e32 v7, 6, v32
	v_add_f32_e32 v17, v58, v59
	v_pk_mul_f32 v[58:59], v[2:3], v[60:61] op_sel_hi:[0,1]
	v_pk_mul_f32 v[58:59], v[72:73], v[58:59]
	v_cvt_pk_bf16_f32 v106, v9, v17
	v_cvt_f32_i32_e32 v7, v7
	v_pk_mul_f32 v[60:61], v[64:65], v[58:59]
	v_or_b32_e32 v11, 7, v32
	v_sub_f32_e32 v19, v60, v61
	v_mov_b32_e32 v60, v65
	v_mov_b32_e32 v61, v64
	v_pk_mul_f32 v[58:59], v[60:61], v[58:59]
	v_cvt_pk_bf16_f32 v102, v13, v19
	v_mul_f32_e32 v9, 0xbed49a78, v7
	v_add_f32_e32 v23, v58, v59
	v_cvt_pk_bf16_f32 v98, v15, v23
	flat_load_dwordx2 v[58:59], v[34:35] offset:24
	flat_load_dwordx2 v[60:61], v[34:35] offset:152
	flat_load_dwordx2 v[62:63], v[34:35] offset:280
	flat_load_dwordx2 v[64:65], v[34:35] offset:408
	v_cmp_gt_f32_e32 vcc, s43, v9
	v_cvt_f32_i32_e32 v11, v11
	v_mul_f32_e32 v15, 0xbed49a78, v11
	v_cndmask_b32_e32 v9, 0, v189, vcc
	v_fmac_f32_e32 v9, 0xbed49a78, v7
	v_exp_f32_e32 v7, v9
	v_cndmask_b32_e32 v9, 0, v190, vcc
	v_cmp_gt_f32_e32 vcc, s43, v15
	v_ldexp_f32 v7, v7, v9
	v_mul_f32_e32 v9, v7, v3
	v_mul_f32_e32 v9, 0.15915494, v9
	v_sin_f32_e32 v67, v9
	v_cos_f32_e32 v66, v9
	v_mul_f32_e32 v7, v7, v6
	v_cndmask_b32_e32 v15, 0, v189, vcc
	v_mul_f32_e32 v7, 0.15915494, v7
	v_fmac_f32_e32 v15, 0xbed49a78, v11
	v_sin_f32_e32 v69, v7
	v_cos_f32_e32 v68, v7
	v_exp_f32_e32 v11, v15
	v_cndmask_b32_e32 v17, 0, v190, vcc
	v_ldexp_f32 v11, v11, v17
	v_mul_f32_e32 v17, v11, v3
	v_mul_f32_e32 v17, 0.15915494, v17
	v_mul_f32_e32 v11, v11, v6
	v_mul_f32_e32 v11, 0.15915494, v11
	s_waitcnt vmcnt(0) lgkmcnt(0)
; #define QW(d0) (u ? __uint_as_float(qv[d0][jp] & 0xffff0000u) : __uint_as_float(qv[d0][jp] << 16))
; template <typename TQ>
; __device__ __forceinline__ void attn_dense_body(const TQ* __restrict__ Qb, const bf16* __restrict__ Kh, const bf16* __restrict__ Vh,
;                                                 unsigned short* __restrict__ Ob, int seq, char* lds, const float* __restrict__ qg, int pos0) {
;     ...
;       for (int jp = 0; jp < 4; ++jp) { float o[4][2];
; #pragma unroll
;         for (int u = 0; u < 2; ++u) { const int jj = 2 * jp + u, e0 = 16 * dd + 8 * hi2 + jj;
;           const float invf = exp2f(-(float)e0 * (13.287712379549449f / 32.0f));
;           const float ar = prow * invf, ac = pcol * invf;
;           const float sr_ = __sinf(ar), cr_ = __cosf(ar), sc_ = __sinf(ac), cc_ = __cosf(ac);
;     ...
;           const float a1 = QW(dd) * ri * qg2[e0], a2 = QW(dd + 2) * ri * qg2[32 + e0], b1 = QW(4 + dd) * ri * qg2[64 + e0], b2 = QW(6 + dd) * ri * qg2[96 + e0];
;     ...
;           o[0][u] = a1 * cr_ - a2 * sr_; o[1][u] = a2 * cr_ + a1 * sr_; o[2][u] = b1 * cc_ - b2 * sc_; o[3][u] = b2 * cc_ + b1 * sc_; }
;         qv[dd][jp] = cvtpk(o[0][0], o[0][1]); qv[dd + 2][jp] = cvtpk(o[1][0], o[1][1]); qv[4 + dd][jp] = cvtpk(o[2][0], o[2][1]); qv[6 + dd][jp] = cvtpk(o[3][0], o[3][1]); }
	v_mov_b32_e32 v70, v58
	v_mov_b32_e32 v71, v60
	v_pk_mul_f32 v[52:53], v[70:71], v[52:53]
	v_mov_b32_e32 v60, v59
	v_pk_mul_f32 v[70:71], v[66:67], v[52:53]
	v_pk_mul_f32 v[48:49], v[60:61], v[48:49]
	v_sub_f32_e32 v7, v70, v71
	v_mov_b32_e32 v70, v67
	v_mov_b32_e32 v71, v66
	v_pk_mul_f32 v[52:53], v[70:71], v[52:53]
	v_and_b32_e32 v70, 63, v74
	v_add_f32_e32 v9, v52, v53
	v_pk_mul_f32 v[52:53], v[2:3], v[54:55] op_sel_hi:[0,1]
	v_mov_b32_e32 v54, v62
	v_mov_b32_e32 v55, v64
	v_pk_mul_f32 v[52:53], v[54:55], v[52:53]
	v_mov_b32_e32 v64, v63
	v_pk_mul_f32 v[54:55], v[68:69], v[52:53]
	s_nop 0
	v_sub_f32_e32 v13, v54, v55
	v_mov_b32_e32 v54, v69
	v_mov_b32_e32 v55, v68
	v_pk_mul_f32 v[52:53], v[54:55], v[52:53]
	v_sin_f32_e32 v55, v11
	v_add_f32_e32 v15, v52, v53
	v_sin_f32_e32 v53, v17
	v_cos_f32_e32 v52, v17
	v_cos_f32_e32 v54, v11
	v_ashrrev_i32_e32 v68, 4, v74
	v_add_u32_e32 v66, 0xa0, v68
	v_pk_mul_f32 v[58:59], v[52:53], v[48:49]
	s_nop 0
	v_sub_f32_e32 v11, v58, v59
	v_mov_b32_e32 v58, v53
	v_mov_b32_e32 v59, v52
	v_pk_mul_f32 v[48:49], v[58:59], v[48:49]
	v_cvt_pk_bf16_f32 v111, v7, v11
	v_add_u32_e32 v7, 16, v32
	v_add_f32_e32 v17, v48, v49
	v_pk_mul_f32 v[48:49], v[2:3], v[50:51] op_sel_hi:[0,1]
	v_pk_mul_f32 v[48:49], v[64:65], v[48:49]
	v_cvt_pk_bf16_f32 v107, v9, v17
	v_cvt_f32_i32_e32 v7, v7
	v_pk_mul_f32 v[50:51], v[54:55], v[48:49]
	v_add_u32_e32 v11, 17, v32
	v_sub_f32_e32 v19, v50, v51
	v_mov_b32_e32 v50, v55
	v_mov_b32_e32 v51, v54
	v_pk_mul_f32 v[48:49], v[50:51], v[48:49]
	v_cvt_pk_bf16_f32 v103, v13, v19
	v_mul_f32_e32 v9, 0xbed49a78, v7
	v_add_f32_e32 v23, v48, v49
	v_cvt_pk_bf16_f32 v99, v15, v23
	flat_load_dwordx2 v[48:49], v[34:35] offset:64
	flat_load_dwordx2 v[50:51], v[34:35] offset:192
	flat_load_dwordx2 v[52:53], v[34:35] offset:320
	flat_load_dwordx2 v[54:55], v[34:35] offset:448
	v_cmp_gt_f32_e32 vcc, s43, v9
	v_cvt_f32_i32_e32 v11, v11
	v_mov_b32_e32 v23, v47
	v_cndmask_b32_e32 v9, 0, v189, vcc
	v_fmac_f32_e32 v9, 0xbed49a78, v7
	v_exp_f32_e32 v7, v9
	v_cndmask_b32_e32 v9, 0, v190, vcc
	v_mul_f32_e32 v15, 0xbed49a78, v11
	v_cmp_gt_f32_e32 vcc, s43, v15
	v_ldexp_f32 v7, v7, v9
	v_mul_f32_e32 v9, v7, v3
	v_mul_f32_e32 v9, 0.15915494, v9
	v_sin_f32_e32 v57, v9
	v_cos_f32_e32 v56, v9
	v_mul_f32_e32 v7, v7, v6
	v_cndmask_b32_e32 v15, 0, v189, vcc
	v_mul_f32_e32 v7, 0.15915494, v7
	v_fmac_f32_e32 v15, 0xbed49a78, v11
	v_sin_f32_e32 v59, v7
	v_cos_f32_e32 v58, v7
	v_exp_f32_e32 v11, v15
	v_cndmask_b32_e32 v17, 0, v190, vcc
	v_pk_mul_f32 v[22:23], v[2:3], v[22:23] op_sel_hi:[0,1]
	v_ldexp_f32 v11, v11, v17
	v_mul_f32_e32 v17, v11, v3
	v_mul_f32_e32 v17, 0.15915494, v17
	v_mul_f32_e32 v11, v11, v6
	v_mul_f32_e32 v11, 0.15915494, v11
	s_waitcnt vmcnt(0) lgkmcnt(0)
	v_mov_b32_e32 v60, v48
	v_mov_b32_e32 v61, v50
	v_pk_mul_f32 v[42:43], v[60:61], v[42:43]
	v_mov_b32_e32 v50, v49
	v_pk_mul_f32 v[60:61], v[56:57], v[42:43]
	v_pk_mul_f32 v[40:41], v[50:51], v[40:41]
	v_sub_f32_e32 v7, v60, v61
	v_mov_b32_e32 v60, v57
	v_mov_b32_e32 v61, v56
	v_pk_mul_f32 v[42:43], v[60:61], v[42:43]
	s_nop 0
	v_add_f32_e32 v9, v42, v43
	v_pk_mul_f32 v[42:43], v[2:3], v[44:45] op_sel_hi:[0,1]
	v_mov_b32_e32 v44, v52
	v_mov_b32_e32 v45, v54
	v_pk_mul_f32 v[42:43], v[44:45], v[42:43]
	v_mov_b32_e32 v54, v53
	v_pk_mul_f32 v[44:45], v[58:59], v[42:43]
	v_pk_mul_f32 v[22:23], v[54:55], v[22:23]
	v_sub_f32_e32 v13, v44, v45
	v_mov_b32_e32 v44, v59
	v_mov_b32_e32 v45, v58
	v_pk_mul_f32 v[42:43], v[44:45], v[42:43]
	v_sin_f32_e32 v45, v11
	v_add_f32_e32 v15, v42, v43
	v_sin_f32_e32 v43, v17
	v_cos_f32_e32 v42, v17
	v_cos_f32_e32 v44, v11
	v_add_u32_e32 v52, 0x60, v68
	v_pk_mul_f32 v[48:49], v[42:43], v[40:41]
	s_nop 0
	v_sub_f32_e32 v11, v48, v49
	v_mov_b32_e32 v48, v43
	v_mov_b32_e32 v49, v42
	v_pk_mul_f32 v[40:41], v[48:49], v[40:41]
	v_cvt_pk_bf16_f32 v124, v7, v11
	v_add_u32_e32 v7, 18, v32
	v_add_f32_e32 v17, v40, v41
	v_pk_mul_f32 v[40:41], v[44:45], v[22:23]
	v_cvt_pk_bf16_f32 v120, v9, v17
	v_cvt_f32_i32_e32 v7, v7
	v_sub_f32_e32 v19, v40, v41
	v_mov_b32_e32 v40, v45
	v_mov_b32_e32 v41, v44
	v_pk_mul_f32 v[22:23], v[40:41], v[22:23]
	v_cvt_pk_bf16_f32 v116, v13, v19
	v_mul_f32_e32 v9, 0xbed49a78, v7
	v_add_f32_e32 v22, v22, v23
	v_cvt_pk_bf16_f32 v112, v15, v22
	flat_load_dwordx2 v[22:23], v[34:35] offset:72
	flat_load_dwordx2 v[40:41], v[34:35] offset:200
	flat_load_dwordx2 v[42:43], v[34:35] offset:328
	flat_load_dwordx2 v[44:45], v[34:35] offset:456
	v_cmp_gt_f32_e32 vcc, s43, v9
	v_add_u32_e32 v11, 19, v32
	v_cvt_f32_i32_e32 v11, v11
	v_cndmask_b32_e32 v9, 0, v189, vcc
	v_fmac_f32_e32 v9, 0xbed49a78, v7
	v_exp_f32_e32 v7, v9
	v_cndmask_b32_e32 v9, 0, v190, vcc
	v_mul_f32_e32 v15, 0xbed49a78, v11
	v_cmp_gt_f32_e32 vcc, s43, v15
	v_ldexp_f32 v7, v7, v9
	v_mul_f32_e32 v9, v7, v3
	v_mul_f32_e32 v9, 0.15915494, v9
	v_sin_f32_e32 v47, v9
	v_cos_f32_e32 v46, v9
	v_mul_f32_e32 v7, v7, v6
	v_cndmask_b32_e32 v15, 0, v189, vcc
	v_mul_f32_e32 v7, 0.15915494, v7
	v_fmac_f32_e32 v15, 0xbed49a78, v11
	v_sin_f32_e32 v49, v7
	v_cos_f32_e32 v48, v7
	v_exp_f32_e32 v11, v15
	v_mov_b32_e32 v19, v20
	v_pk_mul_f32 v[18:19], v[2:3], v[18:19] op_sel_hi:[0,1]
	v_cndmask_b32_e32 v17, 0, v190, vcc
	v_ldexp_f32 v11, v11, v17
	v_mul_f32_e32 v17, v11, v3
	v_mul_f32_e32 v17, 0.15915494, v17
	v_mul_f32_e32 v11, v11, v6
	v_mul_f32_e32 v11, 0.15915494, v11
	s_waitcnt vmcnt(0) lgkmcnt(0)
; #define QW(d0) (u ? __uint_as_float(qv[d0][jp] & 0xffff0000u) : __uint_as_float(qv[d0][jp] << 16))
; template <typename TQ>
; __device__ __forceinline__ void attn_dense_body(const TQ* __restrict__ Qb, const bf16* __restrict__ Kh, const bf16* __restrict__ Vh,
;                                                 unsigned short* __restrict__ Ob, int seq, char* lds, const float* __restrict__ qg, int pos0) {
;     ...
;       for (int jp = 0; jp < 4; ++jp) { float o[4][2];
; #pragma unroll
;         for (int u = 0; u < 2; ++u) { const int jj = 2 * jp + u, e0 = 16 * dd + 8 * hi2 + jj;
;           const float invf = exp2f(-(float)e0 * (13.287712379549449f / 32.0f));
;           const float ar = prow * invf, ac = pcol * invf;
;           const float sr_ = __sinf(ar), cr_ = __cosf(ar), sc_ = __sinf(ac), cc_ = __cosf(ac);
;     ...
;           const float a1 = QW(dd) * ri * qg2[e0], a2 = QW(dd + 2) * ri * qg2[32 + e0], b1 = QW(4 + dd) * ri * qg2[64 + e0], b2 = QW(6 + dd) * ri * qg2[96 + e0];
;     ...
;           o[0][u] = a1 * cr_ - a2 * sr_; o[1][u] = a2 * cr_ + a1 * sr_; o[2][u] = b1 * cc_ - b2 * sc_; o[3][u] = b2 * cc_ + b1 * sc_; }
;         qv[dd][jp] = cvtpk(o[0][0], o[0][1]); qv[dd + 2][jp] = cvtpk(o[1][0], o[1][1]); qv[4 + dd][jp] = cvtpk(o[2][0], o[2][1]); qv[6 + dd][jp] = cvtpk(o[3][0], o[3][1]); }
	v_mov_b32_e32 v50, v22
	v_mov_b32_e32 v51, v40
	v_pk_mul_f32 v[38:39], v[50:51], v[38:39]
	v_mov_b32_e32 v40, v23
	v_pk_mul_f32 v[50:51], v[46:47], v[38:39]
	v_pk_mul_f32 v[22:23], v[40:41], v[36:37]
	v_sub_f32_e32 v7, v50, v51
	v_mov_b32_e32 v50, v47
	v_mov_b32_e32 v51, v46
	v_pk_mul_f32 v[38:39], v[50:51], v[38:39]
	s_nop 0
	v_add_f32_e32 v9, v38, v39
	v_mov_b32_e32 v38, v42
	v_mov_b32_e32 v39, v44
	v_pk_mul_f32 v[18:19], v[38:39], v[18:19]
	v_mov_b32_e32 v44, v43
	v_pk_mul_f32 v[38:39], v[48:49], v[18:19]
	s_nop 0
	v_sub_f32_e32 v13, v38, v39
	v_mov_b32_e32 v38, v49
	v_mov_b32_e32 v39, v48
	v_pk_mul_f32 v[18:19], v[38:39], v[18:19]
	v_sin_f32_e32 v39, v11
	v_add_f32_e32 v15, v18, v19
	v_sin_f32_e32 v19, v17
	v_cos_f32_e32 v18, v17
	v_cos_f32_e32 v38, v11
	v_mov_b32_e32 v17, v21
	v_pk_mul_f32 v[16:17], v[2:3], v[16:17] op_sel_hi:[0,1]
	v_pk_mul_f32 v[36:37], v[18:19], v[22:23]
	v_pk_mul_f32 v[16:17], v[16:17], v[44:45]
	v_sub_f32_e32 v11, v36, v37
	v_mov_b32_e32 v36, v19
	v_mov_b32_e32 v37, v18
	v_pk_mul_f32 v[18:19], v[36:37], v[22:23]
	v_cvt_pk_bf16_f32 v125, v7, v11
	v_add_u32_e32 v7, 20, v32
	v_add_f32_e32 v20, v18, v19
	v_pk_mul_f32 v[18:19], v[38:39], v[16:17]
	v_cvt_pk_bf16_f32 v121, v9, v20
	v_cvt_f32_i32_e32 v7, v7
	v_sub_f32_e32 v21, v18, v19
	v_mov_b32_e32 v18, v39
	v_mov_b32_e32 v19, v38
	v_pk_mul_f32 v[16:17], v[18:19], v[16:17]
	v_cvt_pk_bf16_f32 v117, v13, v21
	v_mul_f32_e32 v9, 0xbed49a78, v7
	v_add_f32_e32 v16, v16, v17
	v_cvt_pk_bf16_f32 v113, v15, v16
	flat_load_dwordx2 v[16:17], v[34:35] offset:80
	flat_load_dwordx2 v[18:19], v[34:35] offset:208
	flat_load_dwordx2 v[20:21], v[34:35] offset:336
	flat_load_dwordx2 v[22:23], v[34:35] offset:464
	v_cmp_gt_f32_e32 vcc, s43, v9
	v_mov_b32_e32 v15, v4
	v_add_u32_e32 v4, 21, v32
	v_cndmask_b32_e32 v9, 0, v189, vcc
	v_fmac_f32_e32 v9, 0xbed49a78, v7
	v_exp_f32_e32 v7, v9
	v_cndmask_b32_e32 v9, 0, v190, vcc
	v_cvt_f32_i32_e32 v4, v4
	v_pk_mul_f32 v[14:15], v[2:3], v[14:15] op_sel_hi:[0,1]
	v_ldexp_f32 v7, v7, v9
	v_mul_f32_e32 v9, v7, v3
	v_mul_f32_e32 v9, 0.15915494, v9
	v_sin_f32_e32 v37, v9
	v_cos_f32_e32 v36, v9
	v_mul_f32_e32 v13, 0xbed49a78, v4
	v_cmp_gt_f32_e32 vcc, s43, v13
	v_mul_f32_e32 v7, v7, v6
	v_mul_f32_e32 v7, 0.15915494, v7
	v_cndmask_b32_e32 v13, 0, v189, vcc
	v_fmac_f32_e32 v13, 0xbed49a78, v4
	v_sin_f32_e32 v39, v7
	v_cos_f32_e32 v38, v7
	v_exp_f32_e32 v4, v13
	v_cndmask_b32_e32 v13, 0, v190, vcc
	v_lshlrev_b32_e32 v48, 4, v74
	v_ldexp_f32 v4, v4, v13
	v_mul_f32_e32 v13, v4, v3
	v_mul_f32_e32 v13, 0.15915494, v13
	v_mul_f32_e32 v4, v4, v6
	v_mul_f32_e32 v4, 0.15915494, v4
	s_waitcnt vmcnt(0) lgkmcnt(0)
	v_mov_b32_e32 v40, v16
	v_mov_b32_e32 v41, v18
	v_pk_mul_f32 v[30:31], v[30:31], v[40:41]
	v_mov_b32_e32 v18, v17
	v_pk_mul_f32 v[40:41], v[36:37], v[30:31]
	v_pk_mul_f32 v[16:17], v[28:29], v[18:19]
	v_sub_f32_e32 v7, v40, v41
	v_mov_b32_e32 v40, v37
	v_mov_b32_e32 v41, v36
	v_pk_mul_f32 v[30:31], v[40:41], v[30:31]
	s_nop 0
	v_add_f32_e32 v9, v30, v31
	v_mov_b32_e32 v30, v20
	v_mov_b32_e32 v31, v22
	v_pk_mul_f32 v[14:15], v[14:15], v[30:31]
	v_mov_b32_e32 v22, v21
	v_pk_mul_f32 v[30:31], v[38:39], v[14:15]
	s_nop 0
	v_sub_f32_e32 v11, v30, v31
	v_mov_b32_e32 v30, v39
	v_mov_b32_e32 v31, v38
	v_pk_mul_f32 v[14:15], v[30:31], v[14:15]
	v_sin_f32_e32 v31, v4
	v_add_f32_e32 v20, v14, v15
	v_sin_f32_e32 v15, v13
	v_cos_f32_e32 v14, v13
	v_cos_f32_e32 v30, v4
	v_mov_b32_e32 v13, v5
	v_pk_mul_f32 v[4:5], v[2:3], v[12:13] op_sel_hi:[0,1]
	v_pk_mul_f32 v[18:19], v[14:15], v[16:17]
	v_pk_mul_f32 v[4:5], v[4:5], v[22:23]
	v_sub_f32_e32 v28, v18, v19
	v_mov_b32_e32 v18, v15
	v_mov_b32_e32 v19, v14
	v_pk_mul_f32 v[14:15], v[18:19], v[16:17]
	v_pk_mul_f32 v[12:13], v[30:31], v[4:5]
	v_add_f32_e32 v14, v14, v15
	v_sub_f32_e32 v15, v12, v13
	v_mov_b32_e32 v12, v31
	v_mov_b32_e32 v13, v30
	v_pk_mul_f32 v[4:5], v[12:13], v[4:5]
	v_cvt_pk_bf16_f32 v126, v7, v28
	v_cvt_pk_bf16_f32 v122, v9, v14
	v_cvt_pk_bf16_f32 v118, v11, v15
	v_add_u32_e32 v7, 22, v32
	v_add_f32_e32 v4, v4, v5
	v_cvt_pk_bf16_f32 v114, v20, v4
	flat_load_dwordx2 v[4:5], v[34:35] offset:88
	flat_load_dwordx2 v[12:13], v[34:35] offset:216
	flat_load_dwordx2 v[14:15], v[34:35] offset:344
	flat_load_dwordx2 v[16:17], v[34:35] offset:472
	v_cvt_f32_i32_e32 v7, v7
	v_mov_b32_e32 v11, v0
	v_add_u32_e32 v0, 23, v32
	v_cvt_f32_i32_e32 v0, v0
	v_mul_f32_e32 v9, 0xbed49a78, v7
	v_cmp_gt_f32_e32 vcc, s43, v9
	v_pk_mul_f32 v[22:23], v[2:3], v[26:27] op_sel_hi:[0,1]
	v_pk_mul_f32 v[10:11], v[2:3], v[10:11] op_sel_hi:[0,1]
	v_cndmask_b32_e32 v9, 0, v189, vcc
	v_fmac_f32_e32 v9, 0xbed49a78, v7
	v_exp_f32_e32 v7, v9
	v_cndmask_b32_e32 v9, 0, v190, vcc
	v_ldexp_f32 v7, v7, v9
	v_mul_f32_e32 v9, v7, v3
	v_mul_f32_e32 v9, 0.15915494, v9
	v_sin_f32_e32 v19, v9
	v_cos_f32_e32 v18, v9
	v_mul_f32_e32 v7, v7, v6
	v_mul_f32_e32 v7, 0.15915494, v7
	v_sin_f32_e32 v21, v7
	v_cos_f32_e32 v20, v7
	v_mov_b32_e32 v9, v1
	s_waitcnt vmcnt(0) lgkmcnt(0)
; __device__ __forceinline__ int v_st(int k, int c) { const int kk = (k & ~0xC) | ((k & 4) << 1) | ((k & 8) >> 1); return ((kk >> 3) * 4 + (c >> 5)) * 512 + ((kk & 7) * 32 + (c & 31)) * 2; }
; __device__ __forceinline__ int v_rd_base(int lane) { return ((lane & 3) << 3) | (((lane >> 2) & 3) << 6) | (((lane >> 4) & 1) << 5) | (((lane >> 5) & 1) << 8); }
; #define SLOAD(i, k0) do { sr_[i].vs0 = St::ld8(&Vh[(long)((k0) + sr) * LDK + sc]); sr_[i].vs1 = St::ld8(&Vh[(long)((k0) + 32 + sr) * LDK + sc]); \
;     sr_[i].ks0 = St::ld8(&Kh[(long)((k0) + sr) * LDK + sc]); sr_[i].ks1 = St::ld8(&Kh[(long)((k0) + 32 + sr) * LDK + sc]); } while (0)
; __device__ __forceinline__ void qkt(f32x16& p0, f32x16& p1, const bf16* Ks, const bf16x8* qr, int r32, int hi) {
;   p0 = f32x16{}; p1 = f32x16{};
;   for (int d0 = 0; d0 < 8; ++d0) { int cb = (d0 * 16 + hi * 8) * 2;
;     bf16x8 b0 = *reinterpret_cast<const bf16x8*>((const char*)Ks + KSWZ(r32, cb));
;     bf16x8 b1 = *reinterpret_cast<const bf16x8*>((const char*)Ks + KSWZ(32 + r32, cb));
;     p0 = __builtin_amdgcn_mfma_f32_32x32x16_bf16(b0, qr[d0], p0, 0, 0, 0);
;     p1 = __builtin_amdgcn_mfma_f32_32x32x16_bf16(b1, qr[d0], p1, 0, 0, 0); }
; template <typename TQ>
; __device__ __forceinline__ void attn_dense_body(const TQ* __restrict__ Qb, const bf16* __restrict__ Kh, const bf16* __restrict__ Vh,
;                                                 unsigned short* __restrict__ Ob, int seq, char* lds, const float* __restrict__ qg, int pos0) {
;     ...
;         qv[dd][jp] = cvtpk(o[0][0], o[0][1]); qv[dd + 2][jp] = cvtpk(o[1][0], o[1][1]); qv[4 + dd][jp] = cvtpk(o[2][0], o[2][1]); qv[6 + dd][jp] = cvtpk(o[3][0], o[3][1]); }
; #pragma unroll
;     for (int d0 = 0; d0 < 8; ++d0) qr[d0] = *reinterpret_cast<bf16x8*>(&qv[d0]);
;     ...
;   }
;   const int sr = tid >> 4, sc = (tid & 15) * 8, vst0 = v_st(sr, sc), vst1 = v_st(32 + sr, sc);
;   const int vb0 = (int)(uintptr_t)V_lds + v_rd_base(lane);
;   struct { typename St::T vs0, vs1, ks0, ks1; } sr_[SDEPTH];
;     ...
;   f32x16 pA0, pA1, pB0, pB1; float mnA, mnB, alA, alB; bf16x8 pa0, pa1, pa2, pa3; const int NT = seq / KVBLK;
;   constexpr int SE = 0, SO = SDEPTH - 1;
;   SLOAD(SE, 0); asm volatile("s_waitcnt vmcnt(0)" ::: "memory"); SWRITE(0, SE); __syncthreads();
;   qkt(pA0, pA1, K_lds, qr, r32, hi); partialSM(pA0, pA1, m_reg, mnA, alA);
	v_mov_b32_e32 v26, v4
	v_mul_f32_e32 v4, 0xbed49a78, v0
	v_cmp_gt_f32_e32 vcc, s43, v4
	v_mov_b32_e32 v27, v12
	v_pk_mul_f32 v[22:23], v[22:23], v[26:27]
	v_cndmask_b32_e32 v4, 0, v189, vcc
	v_fmac_f32_e32 v4, 0xbed49a78, v0
	v_exp_f32_e32 v0, v4
	v_pk_mul_f32 v[26:27], v[18:19], v[22:23]
	v_cndmask_b32_e32 v4, 0, v190, vcc
	v_sub_f32_e32 v28, v26, v27
	v_mov_b32_e32 v26, v19
	v_mov_b32_e32 v27, v18
	v_pk_mul_f32 v[18:19], v[26:27], v[22:23]
	v_ldexp_f32 v0, v0, v4
	v_add_f32_e32 v22, v18, v19
	v_mov_b32_e32 v18, v14
	v_mov_b32_e32 v19, v16
	v_pk_mul_f32 v[10:11], v[10:11], v[18:19]
	v_mul_f32_e32 v3, v0, v3
	v_pk_mul_f32 v[18:19], v[20:21], v[10:11]
	v_mul_f32_e32 v3, 0.15915494, v3
	v_sub_f32_e32 v14, v18, v19
	v_mov_b32_e32 v18, v21
	v_mov_b32_e32 v19, v20
	v_mul_f32_e32 v0, v0, v6
	v_sin_f32_e32 v7, v3
	v_cos_f32_e32 v6, v3
	v_pk_mul_f32 v[10:11], v[18:19], v[10:11]
	v_mul_f32_e32 v0, 0.15915494, v0
	v_add_f32_e32 v20, v10, v11
	v_sin_f32_e32 v11, v0
	v_cos_f32_e32 v10, v0
	v_pk_mul_f32 v[18:19], v[2:3], v[24:25] op_sel_hi:[0,1]
	v_mov_b32_e32 v12, v5
	v_pk_mul_f32 v[4:5], v[18:19], v[12:13]
	v_pk_mul_f32 v[0:1], v[2:3], v[8:9] op_sel_hi:[0,1]
	v_pk_mul_f32 v[12:13], v[6:7], v[4:5]
	v_mov_b32_e32 v16, v15
	v_sub_f32_e32 v18, v12, v13
	v_mov_b32_e32 v12, v7
	v_mov_b32_e32 v13, v6
	v_pk_mul_f32 v[0:1], v[0:1], v[16:17]
	v_pk_mul_f32 v[4:5], v[12:13], v[4:5]
	v_pk_mul_f32 v[2:3], v[10:11], v[0:1]
	v_add_f32_e32 v4, v4, v5
	v_sub_f32_e32 v5, v2, v3
	v_mov_b32_e32 v2, v11
	v_mov_b32_e32 v3, v10
	v_pk_mul_f32 v[0:1], v[2:3], v[0:1]
	v_lshlrev_b32_e32 v16, 3, v74
	v_add_f32_e32 v0, v0, v1
	v_cvt_pk_bf16_f32 v127, v28, v18
	v_cvt_pk_bf16_f32 v123, v22, v4
	v_cvt_pk_bf16_f32 v119, v14, v5
	v_cvt_pk_bf16_f32 v115, v20, v0
	v_and_b32_e32 v69, 0x78, v16
	v_mad_i64_i32 v[0:1], s[10:11], v68, s44, 0
	v_or_b32_e32 v0, v0, v69
	v_lshl_add_u64 v[8:9], v[0:1], 1, s[4:5]
	v_add_u32_e32 v17, 32, v68
	global_load_dwordx4 v[0:3], v[8:9], off offset:2560
	v_mad_i64_i32 v[4:5], s[10:11], v17, s44, 0
	v_or_b32_e32 v4, v4, v69
	v_lshl_add_u64 v[12:13], v[4:5], 1, s[4:5]
	global_load_dwordx4 v[4:7], v[12:13], off offset:2560
	s_nop 0
	global_load_dwordx4 v[8:11], v[8:9], off offset:2048
	s_nop 0
	global_load_dwordx4 v[12:15], v[12:13], off offset:2048
	v_and_b32_e32 v18, 0xfffff0, v68
	v_lshlrev_b32_e32 v19, 1, v68
	v_and_or_b32 v18, v19, 8, v18
	v_lshrrev_b32_e32 v19, 1, v68
	v_lshrrev_b32_e32 v18, 1, v18
	v_bfe_u32 v16, v16, 5, 2
	v_and_b32_e32 v20, 3, v68
	v_or_b32_e32 v18, v18, v16
	v_and_or_b32 v19, v19, 4, v20
	v_lshlrev_b32_e32 v20, 1, v69
	v_and_b32_e32 v22, 0xfffff0, v17
	v_lshlrev_b32_e32 v23, 1, v17
	v_lshlrev_b32_e32 v18, 9, v18
	v_lshlrev_b32_e32 v19, 6, v19
	v_and_b32_e32 v21, 48, v20
	v_and_or_b32 v22, v23, 8, v22
	v_or3_b32 v18, v18, v19, v21
	v_lshrrev_b32_e32 v22, 1, v22
	v_or_b32_e32 v16, v22, v16
	v_add_u32_e32 v202, 0, v18
	v_lshlrev_b32_e32 v16, 9, v16
	s_waitcnt vmcnt(0)
	v_or3_b32 v16, v16, v19, v21
	v_add_u32_e32 v203, 0, v16
	s_mov_b32 s10, s8
	s_mov_b32 s11, s8
	s_waitcnt vmcnt(3)
	ds_write_b128 v202, v[0:3]
	v_lshlrev_b32_e32 v0, 8, v68
	v_and_b32_e32 v1, 0x70, v74
	v_bitop3_b32 v0, v20, v0, v1 bitop3:0xde
	v_add_u32_e32 v204, 0, v0
	v_lshlrev_b32_e32 v0, 8, v17
	s_waitcnt vmcnt(2)
	ds_write_b128 v203, v[4:7]
	s_waitcnt vmcnt(1)
	ds_write_b128 v204, v[8:11] offset:32768
	v_bitop3_b32 v0, v20, v0, v1 bitop3:0xde
	v_lshlrev_b32_e32 v8, 8, v197
	v_and_b32_e32 v9, 0x70, v48
	v_add_u32_e32 v205, 0, v0
	v_bitop3_b32 v0, v182, v8, v9 bitop3:0xde
	v_add_u32_e32 v206, 0, v0
	s_waitcnt vmcnt(0)
	ds_write_b128 v205, v[12:15] offset:32768
	s_waitcnt lgkmcnt(0)
	s_barrier
	ds_read_b128 v[0:3], v206 offset:32768
	ds_read_b128 v[4:7], v206 offset:40960
	s_waitcnt lgkmcnt(1)
	s_setprio 1
	v_mfma_f32_32x32x16_bf16 v[32:47], v[0:3], v[108:111], 0
	s_setprio 0
	v_or_b32_e32 v0, 32, v182
	v_bitop3_b32 v0, v0, v8, v9 bitop3:0xde
	v_add_u32_e32 v207, 0, v0
	v_lshlrev_b32_e32 v10, 3, v70
	v_lshlrev_b32_e32 v12, 1, v74
	s_waitcnt lgkmcnt(0)
	s_setprio 1
	v_mfma_f32_32x32x16_bf16 v[16:31], v[4:7], v[108:111], 0
	s_setprio 0
	ds_read_b128 v[0:3], v207 offset:32768
	ds_read_b128 v[4:7], v207 offset:40960
	s_waitcnt lgkmcnt(1)
	s_setprio 1
	v_mfma_f32_32x32x16_bf16 v[32:47], v[0:3], v[124:127], v[32:47]
	s_setprio 0
	v_or_b32_e32 v0, 64, v182
	v_bitop3_b32 v0, v0, v8, v9 bitop3:0xde
	v_add_u32_e32 v208, 0, v0
	s_waitcnt lgkmcnt(0)
	s_setprio 1
	v_mfma_f32_32x32x16_bf16 v[16:31], v[4:7], v[124:127], v[16:31]
	s_setprio 0
	ds_read_b128 v[0:3], v208 offset:32768
	ds_read_b128 v[4:7], v208 offset:40960
	s_waitcnt lgkmcnt(1)
	s_setprio 1
	v_mfma_f32_32x32x16_bf16 v[32:47], v[0:3], v[104:107], v[32:47]
	s_setprio 0
	v_or_b32_e32 v0, 0x60, v182
	v_bitop3_b32 v0, v0, v8, v9 bitop3:0xde
	v_add_u32_e32 v209, 0, v0
	s_waitcnt lgkmcnt(0)
	s_setprio 1
	v_mfma_f32_32x32x16_bf16 v[16:31], v[4:7], v[104:107], v[16:31]
	s_setprio 0
	ds_read_b128 v[0:3], v209 offset:32768
	ds_read_b128 v[4:7], v209 offset:40960
	s_waitcnt lgkmcnt(1)
	s_setprio 1
	v_mfma_f32_32x32x16_bf16 v[32:47], v[0:3], v[120:123], v[32:47]
	s_setprio 0
	v_or_b32_e32 v0, 0x80, v182
	v_bitop3_b32 v0, v0, v8, v9 bitop3:0xde
	v_add_u32_e32 v210, 0, v0
	s_waitcnt lgkmcnt(0)
	s_setprio 1
	v_mfma_f32_32x32x16_bf16 v[16:31], v[4:7], v[120:123], v[16:31]
	s_setprio 0
	ds_read_b128 v[0:3], v210 offset:32768
	ds_read_b128 v[4:7], v210 offset:40960
	s_waitcnt lgkmcnt(1)
	s_setprio 1
	v_mfma_f32_32x32x16_bf16 v[32:47], v[0:3], v[100:103], v[32:47]
	s_setprio 0
	v_or_b32_e32 v0, 0xa0, v182
	v_bitop3_b32 v0, v0, v8, v9 bitop3:0xde
	v_add_u32_e32 v211, 0, v0
	ds_read_b128 v[0:3], v211 offset:32768
	s_waitcnt lgkmcnt(1)
; __device__ __forceinline__ void partialSM(f32x16& p0, f32x16& p1, float& m_reg, float& mn, float& alpha) {
;   constexpr float C = SCALE * 1.4426950408889634f;
;   float pmax = p0[0]; for (int r = 1; r < 16; ++r) pmax = fmaxf(pmax, p0[r]); for (int r = 0; r < 16; ++r) pmax = fmaxf(pmax, p1[r]);
;   { auto rr = __builtin_amdgcn_permlane32_swap(__float_as_uint(pmax), __float_as_uint(pmax), false, false);
;     pmax = fmaxf(__uint_as_float(rr[0]), __uint_as_float(rr[1])); }
;   if (__builtin_expect(__all(pmax - m_reg <= THR / SCALE), 1)) { mn = m_reg; alpha = 1.f; }
;   else { mn = fmaxf(m_reg, pmax); alpha = __builtin_amdgcn_exp2f((m_reg - mn) * C); m_reg = mn; }
;   float mnC = -mn * C;
;   for (int r = 0; r < 16; ++r) p0[r] = fmaf(p0[r], C, mnC); for (int r = 0; r < 16; ++r) p1[r] = fmaf(p1[r], C, mnC);
;   for (int r = 0; r < 16; ++r) p0[r] = __builtin_amdgcn_exp2f(p0[r]);
; }
; __device__ __forceinline__ void finishSM(f32x16& p0, f32x16& p1, float alpha, float& l_reg, bf16x8& pa0, bf16x8& pa1, bf16x8& pa2, bf16x8& pa3) {
;   for (int r = 0; r < 16; ++r) p1[r] = __builtin_amdgcn_exp2f(p1[r]);
;   float ps = 0; for (int r = 0; r < 16; ++r) ps += p0[r]; for (int r = 0; r < 16; ++r) ps += p1[r];
;   { auto rr = __builtin_amdgcn_permlane32_swap(__float_as_uint(ps), __float_as_uint(ps), false, false);
;     ps = __uint_as_float(rr[0]) + __uint_as_float(rr[1]); }
;   l_reg = l_reg * alpha + ps;
;     ...
;   PK4(p0, 0, pa0); PK4(p0, 8, pa1); PK4(p1, 0, pa2); PK4(p1, 8, pa3);
;     ...
; }
; __device__ __forceinline__ void qkt(f32x16& p0, f32x16& p1, const bf16* Ks, const bf16x8* qr, int r32, int hi) {
;   p0 = f32x16{}; p1 = f32x16{};
;   for (int d0 = 0; d0 < 8; ++d0) { int cb = (d0 * 16 + hi * 8) * 2;
;     bf16x8 b0 = *reinterpret_cast<const bf16x8*>((const char*)Ks + KSWZ(r32, cb));
;     bf16x8 b1 = *reinterpret_cast<const bf16x8*>((const char*)Ks + KSWZ(32 + r32, cb));
;     p0 = __builtin_amdgcn_mfma_f32_32x32x16_bf16(b0, qr[d0], p0, 0, 0, 0);
;     p1 = __builtin_amdgcn_mfma_f32_32x32x16_bf16(b1, qr[d0], p1, 0, 0, 0); }
	s_setprio 1
	v_mfma_f32_32x32x16_bf16 v[16:31], v[4:7], v[100:103], v[16:31]
	s_setprio 0
	v_and_b32_e32 v4, 0x3fffffc0, v74
	v_lshl_add_u32 v185, v4, 2, s40
	ds_read_b128 v[4:7], v211 offset:40960
	v_lshl_add_u32 v198, v197, 2, v185
	s_waitcnt lgkmcnt(1)
	s_setprio 1
	v_mfma_f32_32x32x16_bf16 v[32:47], v[0:3], v[116:119], v[32:47]
	s_setprio 0
	v_and_b32_e32 v0, 0xc0, v48
	v_and_or_b32 v11, v10, 24, v0
	v_or_b32_e32 v0, 0xc0, v182
	v_bitop3_b32 v0, v0, v8, v9 bitop3:0xde
	v_add_u32_e32 v212, 0, v0
	ds_read_b128 v[0:3], v212 offset:32768
	s_waitcnt lgkmcnt(1)
	s_setprio 1
	v_mfma_f32_32x32x16_bf16 v[16:31], v[4:7], v[116:119], v[16:31]
	s_setprio 0
	v_and_b32_e32 v4, 32, v12
	v_and_b32_e32 v5, 0x100, v10
	v_or3_b32 v71, v11, v4, v5
	ds_read_b128 v[4:7], v212 offset:40960
	v_add_u32_e32 v201, s59, v71
	s_waitcnt lgkmcnt(1)
	s_setprio 1
	v_mfma_f32_32x32x16_bf16 v[32:47], v[0:3], v[96:99], v[32:47]
	s_setprio 0
	v_or_b32_e32 v0, 0xe0, v182
	v_bitop3_b32 v0, v0, v8, v9 bitop3:0xde
	v_add_u32_e32 v213, 0, v0
	ds_read_b128 v[0:3], v213 offset:32768
	ds_read_b128 v[48:51], v213 offset:40960
	s_waitcnt lgkmcnt(2)
	s_setprio 1
	v_mfma_f32_32x32x16_bf16 v[16:31], v[4:7], v[96:99], v[16:31]
	s_setprio 0
	s_waitcnt lgkmcnt(1)
	s_setprio 1
	v_mfma_f32_32x32x16_bf16 v[32:47], v[0:3], v[112:115], v[32:47]
	s_setprio 0
	v_mov_b64_e32 v[0:1], s[8:9]
	v_mov_b64_e32 v[2:3], s[10:11]
	v_mov_b64_e32 v[4:5], s[12:13]
	v_mov_b64_e32 v[6:7], s[14:15]
	v_mov_b64_e32 v[8:9], s[16:17]
	v_mov_b64_e32 v[10:11], s[18:19]
	v_mov_b64_e32 v[12:13], s[20:21]
	s_waitcnt lgkmcnt(0)
	s_setprio 1
	v_mfma_f32_32x32x16_bf16 v[16:31], v[48:51], v[112:115], v[16:31]
	s_setprio 0
	s_nop 2
	v_max_f32_e32 v48, v33, v33
	v_max_f32_e32 v49, v32, v32
	v_max_f32_e32 v48, v49, v48
	v_max3_f32 v48, v48, v34, v35
	v_max3_f32 v48, v48, v36, v37
	v_max3_f32 v48, v48, v38, v39
	v_max3_f32 v48, v48, v40, v41
	v_max3_f32 v48, v48, v42, v43
	v_max3_f32 v48, v48, v44, v45
	v_max3_f32 v48, v48, v46, v47
	v_max3_f32 v48, v48, v16, v17
	v_max3_f32 v48, v48, v18, v19
	v_max3_f32 v48, v48, v20, v21
	v_max3_f32 v48, v48, v22, v23
	v_max3_f32 v64, v48, v24, v25
	v_max3_f32 v64, v64, v26, v27
	v_max3_f32 v64, v64, v28, v29
	v_add_u32_e32 v48, 64, v68
	v_max3_f32 v72, v64, v30, v31
	v_add_u32_e32 v64, 0x80, v68
	v_mov_b64_e32 v[14:15], s[22:23]
	v_mad_i64_i32 v[48:49], s[10:11], v48, s44, 0
	v_mad_i64_i32 v[52:53], s[10:11], v52, s44, 0
	v_mad_i64_i32 v[64:65], s[10:11], v64, s44, 0
	v_or_b32_e32 v48, v48, v69
	v_or_b32_e32 v52, v52, v69
	v_or_b32_e32 v64, v64, v69
	v_mad_i64_i32 v[66:67], s[10:11], v66, s44, 0
	v_lshl_add_u64 v[56:57], v[48:49], 1, s[4:5]
	v_lshl_add_u64 v[60:61], v[52:53], 1, s[4:5]
	v_lshl_add_u64 v[64:65], v[64:65], 1, s[4:5]
	v_or_b32_e32 v66, v66, v69
	global_load_dwordx4 v[48:51], v[56:57], off offset:2560
	global_load_dwordx4 v[52:55], v[60:61], off offset:2560
	s_nop 0
	global_load_dwordx4 v[56:59], v[56:57], off offset:2048
	s_nop 0
	global_load_dwordx4 v[60:63], v[60:61], off offset:2048
	v_lshl_add_u64 v[66:67], v[66:67], 1, s[4:5]
	global_load_dwordx4 v[128:131], v[64:65], off offset:2560
	global_load_dwordx4 v[132:135], v[64:65], off offset:2048
	global_load_dwordx4 v[136:139], v[66:67], off offset:2560
	global_load_dwordx4 v[140:143], v[66:67], off offset:2048
	v_mov_b32_e32 v73, v72
	s_nop 1
	v_permlane32_swap_b32_e32 v72, v73
	v_max_f32_e32 v64, v73, v73
	v_max_f32_e32 v65, v72, v72
	v_max_f32_e32 v64, v65, v64
	v_add_f32_e32 v65, 0x7149f2ca, v64
	v_max_f32_e32 v64, 0xf149f2ca, v64
	v_cmp_ge_f32_e32 vcc, s45, v65
	v_sub_f32_e32 v65, 0xf149f2ca, v64
	v_mul_f32_e32 v65, 0x3e0293ee, v65
	v_exp_f32_e32 v65, v65
	s_cmp_eq_u64 vcc, exec
	s_cselect_b64 vcc, -1, 0
	v_cndmask_b32_e32 v160, v64, v191, vcc
	v_mul_f32_e32 v64, 0xbe0293ee, v160
	v_cndmask_b32_e64 v214, v65, 1.0, vcc
	v_mov_b32_e32 v65, v64
	v_fmac_f32_e32 v65, 0x3e0293ee, v47
	v_fmamk_f32 v32, v32, 0x3e0293ee, v64
	v_fmamk_f32 v33, v33, 0x3e0293ee, v64
	v_fmamk_f32 v34, v34, 0x3e0293ee, v64
	v_fmamk_f32 v35, v35, 0x3e0293ee, v64
	v_fmamk_f32 v36, v36, 0x3e0293ee, v64
	v_fmamk_f32 v37, v37, 0x3e0293ee, v64
	v_fmamk_f32 v38, v38, 0x3e0293ee, v64
	v_fmamk_f32 v39, v39, 0x3e0293ee, v64
	v_fmamk_f32 v40, v40, 0x3e0293ee, v64
	v_fmamk_f32 v41, v41, 0x3e0293ee, v64
	v_fmamk_f32 v42, v42, 0x3e0293ee, v64
	v_fmamk_f32 v43, v43, 0x3e0293ee, v64
	v_fmamk_f32 v44, v44, 0x3e0293ee, v64
	v_fmamk_f32 v45, v45, 0x3e0293ee, v64
	v_fmamk_f32 v46, v46, 0x3e0293ee, v64
	v_pk_fma_f32 v[152:153], v[18:19], s[24:25], v[64:65] op_sel_hi:[1,0,0]
	v_pk_fma_f32 v[154:155], v[16:17], s[24:25], v[64:65] op_sel_hi:[1,0,0]
	v_mad_i64_i32 v[16:17], s[10:11], v68, s39, 0
	v_and_b32_e32 v18, 15, v74
	v_exp_f32_e32 v175, v32
	v_exp_f32_e32 v221, v33
	v_exp_f32_e32 v173, v34
	v_exp_f32_e32 v218, v35
	v_exp_f32_e32 v172, v36
	v_exp_f32_e32 v174, v37
	v_exp_f32_e32 v170, v38
	v_exp_f32_e32 v171, v39
	v_exp_f32_e32 v167, v40
	v_exp_f32_e32 v169, v41
	v_exp_f32_e32 v166, v42
	v_exp_f32_e32 v168, v43
	v_exp_f32_e32 v163, v44
	v_exp_f32_e32 v165, v45
	v_exp_f32_e32 v162, v46
	v_exp_f32_e32 v164, v65
	v_mad_i64_i32 v[16:17], s[10:11], s6, v192, v[16:17]
	v_lshlrev_b32_e32 v18, 4, v18
	s_waitcnt vmcnt(4)
	v_or3_b32 v16, v16, s7, v18
	v_pk_fma_f32 v[150:151], v[30:31], s[24:25], v[64:65] op_sel_hi:[1,0,0]
	v_pk_fma_f32 v[156:157], v[28:29], s[24:25], v[64:65] op_sel_hi:[1,0,0]
	v_pk_fma_f32 v[158:159], v[26:27], s[24:25], v[64:65] op_sel_hi:[1,0,0]
	v_pk_fma_f32 v[144:145], v[24:25], s[24:25], v[64:65] op_sel_hi:[1,0,0]
	v_pk_fma_f32 v[146:147], v[22:23], s[24:25], v[64:65] op_sel_hi:[1,0,0]
	v_pk_fma_f32 v[148:149], v[20:21], s[24:25], v[64:65] op_sel_hi:[1,0,0]
	s_waitcnt vmcnt(7)
	ds_write_b128 v202, v[48:51] offset:16384
	s_waitcnt vmcnt(6)
	ds_write_b128 v203, v[52:55] offset:16384
	s_waitcnt vmcnt(5)
	ds_write_b128 v204, v[56:59] offset:49152
	s_waitcnt vmcnt(4)
	ds_write_b128 v205, v[60:63] offset:49152
	s_addk_i32 s59, 0x4000
	v_lshl_add_u64 v[186:187], s[0:1], 0, v[16:17]
	v_mov_b64_e32 v[62:63], v[14:15]
	v_mov_b64_e32 v[46:47], v[14:15]
	v_mov_b64_e32 v[30:31], v[14:15]
	v_cmp_gt_u32_e64 s[4:5], 32, v70
	v_add_u32_e32 v200, s59, v71
	v_mov_b64_e32 v[60:61], v[12:13]
	v_mov_b64_e32 v[58:59], v[10:11]
	v_mov_b64_e32 v[56:57], v[8:9]
	v_mov_b64_e32 v[54:55], v[6:7]
	v_mov_b64_e32 v[52:53], v[4:5]
	v_mov_b64_e32 v[50:51], v[2:3]
	v_mov_b64_e32 v[48:49], v[0:1]
	v_mov_b64_e32 v[44:45], v[12:13]
	v_mov_b64_e32 v[42:43], v[10:11]
	v_mov_b64_e32 v[40:41], v[8:9]
	v_mov_b64_e32 v[38:39], v[6:7]
	v_mov_b64_e32 v[36:37], v[4:5]
	v_mov_b64_e32 v[34:35], v[2:3]
	v_mov_b64_e32 v[32:33], v[0:1]
	v_mov_b64_e32 v[28:29], v[12:13]
	v_mov_b64_e32 v[26:27], v[10:11]
	v_mov_b64_e32 v[24:25], v[8:9]
	v_mov_b64_e32 v[22:23], v[6:7]
	v_mov_b64_e32 v[20:21], v[4:5]
	v_mov_b64_e32 v[18:19], v[2:3]
	v_mov_b64_e32 v[16:17], v[0:1]
	s_waitcnt lgkmcnt(0)
	s_barrier
; #define SBAR() __builtin_amdgcn_sched_barrier(0)
; #define SLOAD(i, k0) do { sr_[i].vs0 = St::ld8(&Vh[(long)((k0) + sr) * LDK + sc]); sr_[i].vs1 = St::ld8(&Vh[(long)((k0) + 32 + sr) * LDK + sc]); \
;     sr_[i].ks0 = St::ld8(&Kh[(long)((k0) + sr) * LDK + sc]); sr_[i].ks1 = St::ld8(&Kh[(long)((k0) + 32 + sr) * LDK + sc]); } while (0)
; __device__ __forceinline__ void finishSM(f32x16& p0, f32x16& p1, float alpha, float& l_reg, bf16x8& pa0, bf16x8& pa1, bf16x8& pa2, bf16x8& pa3) {
;   for (int r = 0; r < 16; ++r) p1[r] = __builtin_amdgcn_exp2f(p1[r]);
;   float ps = 0; for (int r = 0; r < 16; ++r) ps += p0[r]; for (int r = 0; r < 16; ++r) ps += p1[r];
;   { auto rr = __builtin_amdgcn_permlane32_swap(__float_as_uint(ps), __float_as_uint(ps), false, false);
;     ps = __uint_as_float(rr[0]) + __uint_as_float(rr[1]); }
;   l_reg = l_reg * alpha + ps;
;     ...
;   PK4(p0, 0, pa0); PK4(p0, 8, pa1); PK4(p1, 0, pa2); PK4(p1, 8, pa3);
;     ...
; }
; __device__ __forceinline__ void qkt(f32x16& p0, f32x16& p1, const bf16* Ks, const bf16x8* qr, int r32, int hi) {
;   p0 = f32x16{}; p1 = f32x16{};
;   for (int d0 = 0; d0 < 8; ++d0) { int cb = (d0 * 16 + hi * 8) * 2;
;     bf16x8 b0 = *reinterpret_cast<const bf16x8*>((const char*)Ks + KSWZ(r32, cb));
;     bf16x8 b1 = *reinterpret_cast<const bf16x8*>((const char*)Ks + KSWZ(32 + r32, cb));
;     p0 = __builtin_amdgcn_mfma_f32_32x32x16_bf16(b0, qr[d0], p0, 0, 0, 0);
;     p1 = __builtin_amdgcn_mfma_f32_32x32x16_bf16(b1, qr[d0], p1, 0, 0, 0); }
; template <typename TQ>
; __device__ __forceinline__ void attn_dense_body(const TQ* __restrict__ Qb, const bf16* __restrict__ Kh, const bf16* __restrict__ Vh,
;                                                 unsigned short* __restrict__ Ob, int seq, char* lds, const float* __restrict__ qg, int pos0) {
;     ...
;     SBAR(); qkt(pB0, pB1, (bf16*)((char*)K_lds + SHM_K), qr, r32, hi);
;     finishSM(pA0, pA1, alA, l_reg, pa0, pa1, pa2, pa3); SBAR();
;     SLOAD(SO, (j + SDEPTH) * KVBLK); SBAR();
.LBB0_905:
	ds_read_b128 v[64:67], v206 offset:49152
	ds_read_b128 v[68:71], v206 offset:57344
	ds_read_b128 v[222:225], v207 offset:49152
	ds_read_b128 v[226:229], v207 offset:57344
	v_add_f32_e32 v161, 0, v175
	v_add_f32_e32 v161, v221, v161
	s_waitcnt lgkmcnt(3)
	s_setprio 1
	v_mfma_f32_32x32x16_bf16 v[80:95], v[64:67], v[108:111], 0
	s_setprio 0
	v_add_f32_e32 v161, v173, v161
	v_add_f32_e32 v161, v218, v161
	v_add_f32_e32 v161, v172, v161
	v_add_f32_e32 v161, v174, v161
	v_add_f32_e32 v161, v170, v161
	v_add_f32_e32 v161, v171, v161
	v_add_f32_e32 v161, v167, v161
	s_waitcnt lgkmcnt(2)
	s_setprio 1
	v_mfma_f32_32x32x16_bf16 v[64:79], v[68:71], v[108:111], 0
	s_setprio 0
	v_add_f32_e32 v161, v169, v161
	v_add_f32_e32 v161, v166, v161
	v_add_f32_e32 v161, v168, v161
	v_exp_f32_e32 v154, v154
	v_add_f32_e32 v161, v163, v161
	v_exp_f32_e32 v155, v155
	v_add_f32_e32 v161, v165, v161
	s_waitcnt lgkmcnt(1)
	s_setprio 1
	v_mfma_f32_32x32x16_bf16 v[80:95], v[222:225], v[124:127], v[80:95]
	s_setprio 0
	v_exp_f32_e32 v152, v152
	v_add_f32_e32 v161, v162, v161
	v_exp_f32_e32 v153, v153
	v_add_f32_e32 v161, v164, v161
	v_exp_f32_e32 v148, v148
	v_add_f32_e32 v161, v154, v161
	v_exp_f32_e32 v149, v149
	s_waitcnt lgkmcnt(0)
	s_setprio 1
	v_mfma_f32_32x32x16_bf16 v[64:79], v[226:229], v[124:127], v[64:79]
	s_setprio 0
	ds_read_b128 v[222:225], v208 offset:49152
	ds_read_b128 v[226:229], v208 offset:57344
	v_add_f32_e32 v161, v155, v161
	v_exp_f32_e32 v146, v146
	v_add_f32_e32 v161, v152, v161
	v_exp_f32_e32 v147, v147
	v_add_f32_e32 v161, v153, v161
	v_exp_f32_e32 v144, v144
	s_waitcnt lgkmcnt(1)
	s_setprio 1
	v_mfma_f32_32x32x16_bf16 v[80:95], v[222:225], v[104:107], v[80:95]
	s_setprio 0
	v_add_f32_e32 v161, v148, v161
	v_exp_f32_e32 v145, v145
	v_add_f32_e32 v161, v149, v161
	v_exp_f32_e32 v158, v158
	v_add_f32_e32 v161, v146, v161
	v_exp_f32_e32 v159, v159
	v_add_f32_e32 v161, v147, v161
	s_waitcnt lgkmcnt(0)
	s_setprio 1
	v_mfma_f32_32x32x16_bf16 v[64:79], v[226:229], v[104:107], v[64:79]
	s_setprio 0
	ds_read_b128 v[222:225], v209 offset:49152
	ds_read_b128 v[226:229], v209 offset:57344
	v_exp_f32_e32 v156, v156
	v_add_f32_e32 v161, v144, v161
	v_exp_f32_e32 v157, v157
	v_add_f32_e32 v161, v145, v161
	v_exp_f32_e32 v150, v150
	v_add_f32_e32 v161, v158, v161
	s_waitcnt lgkmcnt(1)
	s_setprio 1
	v_mfma_f32_32x32x16_bf16 v[80:95], v[222:225], v[120:123], v[80:95]
	s_setprio 0
	v_exp_f32_e32 v151, v151
	v_add_f32_e32 v161, v159, v161
	v_add_f32_e32 v161, v156, v161
	v_add_f32_e32 v161, v157, v161
	v_add_f32_e32 v161, v150, v161
	v_add_f32_e32 v215, v151, v161
	v_mov_b32_e32 v216, v215
	s_waitcnt lgkmcnt(0)
	s_setprio 1
	v_mfma_f32_32x32x16_bf16 v[64:79], v[226:229], v[120:123], v[64:79]
	s_setprio 0
	ds_read_b128 v[222:225], v210 offset:49152
	ds_read_b128 v[226:229], v210 offset:57344
	v_permlane32_swap_b32_e32 v215, v216
	s_waitcnt lgkmcnt(1)
	s_setprio 1
	v_mfma_f32_32x32x16_bf16 v[80:95], v[222:225], v[100:103], v[80:95]
	s_setprio 0
	s_waitcnt lgkmcnt(0)
	s_setprio 1
	v_mfma_f32_32x32x16_bf16 v[64:79], v[226:229], v[100:103], v[64:79]
	s_setprio 0
	ds_read_b128 v[222:225], v211 offset:49152
	ds_read_b128 v[226:229], v211 offset:57344
	s_waitcnt lgkmcnt(1)
	s_setprio 1
	v_mfma_f32_32x32x16_bf16 v[80:95], v[222:225], v[116:119], v[80:95]
	s_setprio 0
	s_waitcnt lgkmcnt(0)
	s_setprio 1
	v_mfma_f32_32x32x16_bf16 v[64:79], v[226:229], v[116:119], v[64:79]
	s_setprio 0
	ds_read_b128 v[222:225], v212 offset:49152
	ds_read_b128 v[226:229], v212 offset:57344
	s_waitcnt lgkmcnt(1)
	s_setprio 1
	v_mfma_f32_32x32x16_bf16 v[80:95], v[222:225], v[96:99], v[80:95]
	s_setprio 0
	s_waitcnt lgkmcnt(0)
	s_setprio 1
	v_mfma_f32_32x32x16_bf16 v[64:79], v[226:229], v[96:99], v[64:79]
	s_setprio 0
	ds_read_b128 v[222:225], v213 offset:49152
	ds_read_b128 v[226:229], v213 offset:57344
	v_cvt_pk_bf16_f32 v220, v175, v221
	v_cvt_pk_bf16_f32 v221, v173, v218
	s_waitcnt lgkmcnt(1)
	s_setprio 1
	v_mfma_f32_32x32x16_bf16 v[80:95], v[222:225], v[112:115], v[80:95]
	s_setprio 0
	v_cvt_pk_bf16_f32 v222, v172, v174
	v_cvt_pk_bf16_f32 v223, v170, v171
	v_cvt_pk_bf16_f32 v170, v167, v169
	v_cvt_pk_bf16_f32 v171, v166, v168
	v_cvt_pk_bf16_f32 v172, v163, v165
	v_cvt_pk_bf16_f32 v173, v162, v164
	v_cvt_pk_bf16_f32 v162, v154, v155
	s_waitcnt lgkmcnt(0)
	s_setprio 1
	v_mfma_f32_32x32x16_bf16 v[64:79], v[226:229], v[112:115], v[64:79]
	s_setprio 0
	v_cvt_pk_bf16_f32 v163, v152, v153
	v_cvt_pk_bf16_f32 v164, v148, v149
	v_cvt_pk_bf16_f32 v165, v146, v147
	v_cvt_pk_bf16_f32 v166, v144, v145
	v_cvt_pk_bf16_f32 v167, v158, v159
	v_cvt_pk_bf16_f32 v168, v156, v157
	v_cvt_pk_bf16_f32 v169, v150, v151
	v_permlane32_swap_b32_e32 v220, v222
	v_permlane32_swap_b32_e32 v221, v223
	v_permlane32_swap_b32_e32 v170, v172
	v_permlane32_swap_b32_e32 v171, v173
	v_permlane32_swap_b32_e32 v162, v164
	v_permlane32_swap_b32_e32 v163, v165
	v_permlane32_swap_b32_e32 v166, v168
	v_permlane32_swap_b32_e32 v167, v169
	v_add_co_u32_e32 v148, vcc, s47, v186
	s_nop 1
	v_addc_co_u32_e32 v149, vcc, -1, v187, vcc
	v_add_co_u32_e32 v152, vcc, s48, v186
	s_nop 1
	v_addc_co_u32_e32 v153, vcc, -1, v187, vcc
	global_load_dwordx4 v[144:147], v[148:149], off
	s_nop 0
	global_load_dwordx4 v[148:151], v[148:149], off offset:-512
	s_nop 0
	global_load_dwordx4 v[156:159], v[152:153], off
	s_nop 0
	global_load_dwordx4 v[152:155], v[152:153], off offset:-512
	ds_read_b64_tr_b16 v[224:225], v201 offset:0
	ds_read_b64_tr_b16 v[226:227], v201 offset:0x800
	ds_read_b64_tr_b16 v[228:229], v201 offset:0x1000
	ds_read_b64_tr_b16 v[230:231], v201 offset:0x1800
	ds_read_b64_tr_b16 v[232:233], v201 offset:0x2000
	ds_read_b64_tr_b16 v[234:235], v201 offset:0x2800
	ds_read_b64_tr_b16 v[236:237], v201 offset:0x3000
	ds_read_b64_tr_b16 v[238:239], v201 offset:0x3800
	s_waitcnt lgkmcnt(0)
; #define SBAR() __builtin_amdgcn_sched_barrier(0)
; #define SWAIT() do { if constexpr (SDEPTH == 2) asm volatile("s_waitcnt vmcnt(4)" ::: "memory"); else asm volatile("s_waitcnt vmcnt(0)" ::: "memory"); } while (0)
; #define RESC(a) do { if (__any((a) < 1.f)) { if (hi == 0) al_l[r32] = (a); asm volatile("s_waitcnt lgkmcnt(0)" ::: "memory"); \
;     for (int d = 0; d < 4; ++d) for (int r = 0; r < 16; ++r) o[d][r] *= al_l[crow(r, hi)]; } } while (0)
; template <int D0> __device__ __forceinline__ void pv_one(f32x16& od, int vb, bf16x8 pa0, bf16x8 pa1, bf16x8 pa2, bf16x8 pa3) {
;   const s16x4 l0 = tr_read<v_rd_off(D0, 0, 0)>(vb), h0 = tr_read<v_rd_off(D0, 0, 1)>(vb), l1 = tr_read<v_rd_off(D0, 1, 0)>(vb), h1 = tr_read<v_rd_off(D0, 1, 1)>(vb);
;   const s16x4 l2 = tr_read<v_rd_off(D0, 2, 0)>(vb), h2 = tr_read<v_rd_off(D0, 2, 1)>(vb), l3 = tr_read<v_rd_off(D0, 3, 0)>(vb), h3 = tr_read<v_rd_off(D0, 3, 1)>(vb);
;   asm volatile("s_waitcnt lgkmcnt(0)" ::: "memory"); SBAR();
;     ...
;   od = __builtin_amdgcn_mfma_f32_32x32x16_bf16(pa0, PK(l0, h0), od, 0, 0, 0);
;   od = __builtin_amdgcn_mfma_f32_32x32x16_bf16(pa1, PK(l1, h1), od, 0, 0, 0);
;   od = __builtin_amdgcn_mfma_f32_32x32x16_bf16(pa2, PK(l2, h2), od, 0, 0, 0);
;   od = __builtin_amdgcn_mfma_f32_32x32x16_bf16(pa3, PK(l3, h3), od, 0, 0, 0);
;     ...
; }
; __device__ __forceinline__ void pv_d0(f32x16* o, int vb, bf16x8 pa0, bf16x8 pa1, bf16x8 pa2, bf16x8 pa3) {
;   pv_one<0>(o[0], vb, pa0, pa1, pa2, pa3); pv_one<1>(o[1], vb, pa0, pa1, pa2, pa3); pv_one<2>(o[2], vb, pa0, pa1, pa2, pa3); pv_one<3>(o[3], vb, pa0, pa1, pa2, pa3);
; }
; template <typename TQ>
; __device__ __forceinline__ void attn_dense_body(const TQ* __restrict__ Qb, const bf16* __restrict__ Kh, const bf16* __restrict__ Vh,
;                                                 unsigned short* __restrict__ Ob, int seq, char* lds, const float* __restrict__ qg, int pos0) {
;     ...
;     pv_d0(o, vb0, pa0, pa1, pa2, pa3); partialSM(pB0, pB1, m_reg, mnB, alB);
;     __syncthreads(); SWAIT(); SWRITE(0, SE);
;     RESC(alB); __syncthreads();
	s_nop 0
	s_setprio 1
	v_mfma_f32_32x32x16_bf16 v[0:15], v[220:223], v[224:227], v[0:15]
	s_setprio 0
	ds_read_b64_tr_b16 v[224:225], v201 offset:0x200
	ds_read_b64_tr_b16 v[226:227], v201 offset:0xa00
	s_setprio 1
	v_mfma_f32_32x32x16_bf16 v[0:15], v[170:173], v[228:231], v[0:15]
	s_setprio 0
	ds_read_b64_tr_b16 v[228:229], v201 offset:0x1200
	ds_read_b64_tr_b16 v[230:231], v201 offset:0x1a00
	s_setprio 1
	v_mfma_f32_32x32x16_bf16 v[0:15], v[162:165], v[232:235], v[0:15]
	s_setprio 0
	ds_read_b64_tr_b16 v[232:233], v201 offset:0x2200
	ds_read_b64_tr_b16 v[234:235], v201 offset:0x2a00
	ds_read_b64_tr_b16 v[240:241], v201 offset:0x3200
	ds_read_b64_tr_b16 v[242:243], v201 offset:0x3a00
	s_waitcnt lgkmcnt(0)
	s_setprio 1
	v_mfma_f32_32x32x16_bf16 v[0:15], v[166:169], v[236:239], v[0:15]
	v_mfma_f32_32x32x16_bf16 v[48:63], v[220:223], v[224:227], v[48:63]
	s_setprio 0
	ds_read_b64_tr_b16 v[224:225], v201 offset:0x400
	ds_read_b64_tr_b16 v[226:227], v201 offset:0xc00
	s_setprio 1
	v_mfma_f32_32x32x16_bf16 v[48:63], v[170:173], v[228:231], v[48:63]
	s_setprio 0
	ds_read_b64_tr_b16 v[228:229], v201 offset:0x1400
	ds_read_b64_tr_b16 v[230:231], v201 offset:0x1c00
	s_setprio 1
	v_mfma_f32_32x32x16_bf16 v[48:63], v[162:165], v[232:235], v[48:63]
	s_setprio 0
	ds_read_b64_tr_b16 v[232:233], v201 offset:0x2400
	ds_read_b64_tr_b16 v[234:235], v201 offset:0x2c00
	ds_read_b64_tr_b16 v[236:237], v201 offset:0x3400
	ds_read_b64_tr_b16 v[238:239], v201 offset:0x3c00
	s_waitcnt lgkmcnt(0)
	s_setprio 1
	v_mfma_f32_32x32x16_bf16 v[48:63], v[166:169], v[240:243], v[48:63]
	v_mfma_f32_32x32x16_bf16 v[32:47], v[220:223], v[224:227], v[32:47]
	s_setprio 0
	ds_read_b64_tr_b16 v[224:225], v201 offset:0x600
	ds_read_b64_tr_b16 v[226:227], v201 offset:0xe00
	s_setprio 1
	v_mfma_f32_32x32x16_bf16 v[32:47], v[170:173], v[228:231], v[32:47]
	s_setprio 0
	ds_read_b64_tr_b16 v[228:229], v201 offset:0x1600
	ds_read_b64_tr_b16 v[230:231], v201 offset:0x1e00
	s_setprio 1
	v_mfma_f32_32x32x16_bf16 v[32:47], v[162:165], v[232:235], v[32:47]
	s_setprio 0
	ds_read_b64_tr_b16 v[232:233], v201 offset:0x2600
	ds_read_b64_tr_b16 v[234:235], v201 offset:0x2e00
	ds_read_b64_tr_b16 v[240:241], v201 offset:0x3600
	ds_read_b64_tr_b16 v[242:243], v201 offset:0x3e00
	s_waitcnt lgkmcnt(0)
	s_setprio 1
	v_mfma_f32_32x32x16_bf16 v[32:47], v[166:169], v[236:239], v[32:47]
	v_mfma_f32_32x32x16_bf16 v[16:31], v[220:223], v[224:227], v[16:31]
	s_setprio 0
	v_max_f32_e32 v161, v81, v81
	v_max_f32_e32 v174, v80, v80
	v_max_f32_e32 v161, v174, v161
	v_max3_f32 v161, v161, v82, v83
	v_max3_f32 v161, v161, v84, v85
	v_max3_f32 v161, v161, v86, v87
	v_max3_f32 v161, v161, v88, v89
	v_max3_f32 v161, v161, v90, v91
	s_setprio 1
	v_mfma_f32_32x32x16_bf16 v[16:31], v[170:173], v[228:231], v[16:31]
	s_setprio 0
	v_max3_f32 v161, v161, v92, v93
	v_max3_f32 v161, v161, v94, v95
	v_max3_f32 v161, v161, v64, v65
	v_max3_f32 v161, v161, v66, v67
	v_max3_f32 v161, v161, v68, v69
	v_max3_f32 v161, v161, v70, v71
	v_max3_f32 v161, v161, v72, v73
	v_max3_f32 v161, v161, v74, v75
	s_setprio 1
	v_mfma_f32_32x32x16_bf16 v[16:31], v[162:165], v[232:235], v[16:31]
	s_setprio 0
	v_max3_f32 v161, v161, v76, v77
	v_max3_f32 v161, v161, v78, v79
	v_mov_b32_e32 v170, v161
	s_nop 1
	v_permlane32_swap_b32_e32 v161, v170
	v_max_f32_e32 v162, v170, v170
	v_max_f32_e32 v161, v161, v161
	v_max_f32_e32 v161, v161, v162
	v_max_f32_e32 v163, v160, v160
	v_sub_f32_e32 v162, v161, v160
	v_max_f32_e32 v161, v163, v161
	s_setprio 1
	v_mfma_f32_32x32x16_bf16 v[16:31], v[166:169], v[240:243], v[16:31]
	s_setprio 0
	v_sub_f32_e32 v163, v160, v161
	v_mul_f32_e32 v163, 0x3e0293ee, v163
	v_exp_f32_e32 v163, v163
	v_cmp_ge_f32_e32 vcc, s45, v162
	s_cmp_eq_u64 vcc, exec
	s_cselect_b64 s[6:7], -1, 0
	s_barrier
	s_waitcnt vmcnt(4)
	v_cndmask_b32_e64 v217, v163, 1.0, s[6:7]
	v_cmp_gt_f32_e32 vcc, 1.0, v217
	s_waitcnt vmcnt(7)
	ds_write_b128 v202, v[128:131]
	s_waitcnt vmcnt(5)
	ds_write_b128 v203, v[136:139]
	ds_write_b128 v204, v[132:135] offset:32768
	s_waitcnt vmcnt(4)
	ds_write_b128 v205, v[140:143] offset:32768
	s_cbranch_vccz .LBB0_909
	s_and_saveexec_b64 s[10:11], s[4:5]
	ds_write_b32 v198, v217 offset:128
	s_or_b64 exec, exec, s[10:11]
	s_waitcnt lgkmcnt(0)
	v_add_u32_e32 v174, v185, v182
	ds_read_b128 v[162:165], v174 offset:224
	ds_read_b128 v[166:169], v174 offset:192
	ds_read_b128 v[170:173], v174 offset:160
	ds_read_b128 v[218:221], v174 offset:128
	s_waitcnt lgkmcnt(3)
	v_pk_mul_f32 v[12:13], v[12:13], v[162:163]
	s_waitcnt lgkmcnt(2)
	v_pk_mul_f32 v[8:9], v[8:9], v[166:167]
	s_waitcnt lgkmcnt(1)
	v_pk_mul_f32 v[4:5], v[4:5], v[170:171]
	v_pk_mul_f32 v[14:15], v[14:15], v[164:165]
	v_pk_mul_f32 v[10:11], v[10:11], v[168:169]
	v_pk_mul_f32 v[6:7], v[6:7], v[172:173]
	s_waitcnt lgkmcnt(0)
	v_pk_mul_f32 v[2:3], v[2:3], v[220:221]
	v_pk_mul_f32 v[0:1], v[0:1], v[218:219]
	v_pk_mul_f32 v[60:61], v[60:61], v[162:163]
	v_pk_mul_f32 v[56:57], v[56:57], v[166:167]
	v_pk_mul_f32 v[52:53], v[52:53], v[170:171]
	v_pk_mul_f32 v[62:63], v[62:63], v[164:165]
	v_pk_mul_f32 v[58:59], v[58:59], v[168:169]
	v_pk_mul_f32 v[54:55], v[54:55], v[172:173]
	v_pk_mul_f32 v[50:51], v[50:51], v[220:221]
	v_pk_mul_f32 v[48:49], v[48:49], v[218:219]
	v_pk_mul_f32 v[44:45], v[44:45], v[162:163]
	v_pk_mul_f32 v[40:41], v[40:41], v[166:167]
	v_pk_mul_f32 v[36:37], v[36:37], v[170:171]
	v_pk_mul_f32 v[46:47], v[46:47], v[164:165]
	v_pk_mul_f32 v[42:43], v[42:43], v[168:169]
	v_pk_mul_f32 v[38:39], v[38:39], v[172:173]
	v_pk_mul_f32 v[34:35], v[34:35], v[220:221]
	v_pk_mul_f32 v[32:33], v[32:33], v[218:219]
	v_pk_mul_f32 v[28:29], v[28:29], v[162:163]
	v_pk_mul_f32 v[24:25], v[24:25], v[166:167]
	v_pk_mul_f32 v[20:21], v[20:21], v[170:171]
	v_pk_mul_f32 v[30:31], v[30:31], v[164:165]
	v_pk_mul_f32 v[26:27], v[26:27], v[168:169]
	v_pk_mul_f32 v[22:23], v[22:23], v[172:173]
	v_pk_mul_f32 v[18:19], v[18:19], v[220:221]
	v_pk_mul_f32 v[16:17], v[16:17], v[218:219]
; #define SBAR() __builtin_amdgcn_sched_barrier(0)
; #define SLOAD(i, k0) do { sr_[i].vs0 = St::ld8(&Vh[(long)((k0) + sr) * LDK + sc]); sr_[i].vs1 = St::ld8(&Vh[(long)((k0) + 32 + sr) * LDK + sc]); \
;     sr_[i].ks0 = St::ld8(&Kh[(long)((k0) + sr) * LDK + sc]); sr_[i].ks1 = St::ld8(&Kh[(long)((k0) + 32 + sr) * LDK + sc]); } while (0)
; __device__ __forceinline__ void partialSM(f32x16& p0, f32x16& p1, float& m_reg, float& mn, float& alpha) {
;     ...
;   else { mn = fmaxf(m_reg, pmax); alpha = __builtin_amdgcn_exp2f((m_reg - mn) * C); m_reg = mn; }
;   float mnC = -mn * C;
;   for (int r = 0; r < 16; ++r) p0[r] = fmaf(p0[r], C, mnC); for (int r = 0; r < 16; ++r) p1[r] = fmaf(p1[r], C, mnC);
;   for (int r = 0; r < 16; ++r) p0[r] = __builtin_amdgcn_exp2f(p0[r]);
; }
; __device__ __forceinline__ void finishSM(f32x16& p0, f32x16& p1, float alpha, float& l_reg, bf16x8& pa0, bf16x8& pa1, bf16x8& pa2, bf16x8& pa3) {
;   for (int r = 0; r < 16; ++r) p1[r] = __builtin_amdgcn_exp2f(p1[r]);
;   float ps = 0; for (int r = 0; r < 16; ++r) ps += p0[r]; for (int r = 0; r < 16; ++r) ps += p1[r];
;   { auto rr = __builtin_amdgcn_permlane32_swap(__float_as_uint(ps), __float_as_uint(ps), false, false);
;     ps = __uint_as_float(rr[0]) + __uint_as_float(rr[1]); }
;   l_reg = l_reg * alpha + ps;
;     ...
;   PK4(p0, 0, pa0); PK4(p0, 8, pa1); PK4(p1, 0, pa2); PK4(p1, 8, pa3);
;     ...
; }
; template <typename TQ>
; __device__ __forceinline__ void attn_dense_body(const TQ* __restrict__ Qb, const bf16* __restrict__ Kh, const bf16* __restrict__ Vh,
;                                                 unsigned short* __restrict__ Ob, int seq, char* lds, const float* __restrict__ qg, int pos0) {
;     ...
;     SBAR(); qkt(pA0, pA1, K_lds, qr, r32, hi);
;     finishSM(pB0, pB1, alB, l_reg, pa0, pa1, pa2, pa3); SBAR();
;     if (SDEPTH == 1 || j + 3 < NT) SLOAD(SE, (j + 1 + SDEPTH) * KVBLK); SBAR();
.LBB0_909:
	v_cndmask_b32_e64 v218, v161, v160, s[6:7]
	v_mul_f32_e32 v219, 0xbe0293ee, v218
	v_fmamk_f32 v80, v80, 0x3e0293ee, v219
	v_fmamk_f32 v81, v81, 0x3e0293ee, v219
	v_fmamk_f32 v82, v82, 0x3e0293ee, v219
	v_fmamk_f32 v83, v83, 0x3e0293ee, v219
	v_fmamk_f32 v84, v84, 0x3e0293ee, v219
	v_fmamk_f32 v85, v85, 0x3e0293ee, v219
	v_fmamk_f32 v86, v86, 0x3e0293ee, v219
	v_fmamk_f32 v87, v87, 0x3e0293ee, v219
	v_fmamk_f32 v88, v88, 0x3e0293ee, v219
	v_fmamk_f32 v89, v89, 0x3e0293ee, v219
	v_fmamk_f32 v90, v90, 0x3e0293ee, v219
	v_fmamk_f32 v91, v91, 0x3e0293ee, v219
	v_fmamk_f32 v92, v92, 0x3e0293ee, v219
	v_fmamk_f32 v93, v93, 0x3e0293ee, v219
	v_fmamk_f32 v94, v94, 0x3e0293ee, v219
	v_fmamk_f32 v95, v95, 0x3e0293ee, v219
	v_exp_f32_e32 v160, v80
	v_exp_f32_e32 v175, v81
	v_exp_f32_e32 v161, v82
	v_exp_f32_e32 v174, v83
	v_exp_f32_e32 v162, v84
	v_exp_f32_e32 v173, v85
	v_exp_f32_e32 v163, v86
	v_exp_f32_e32 v172, v87
	v_exp_f32_e32 v164, v88
	v_exp_f32_e32 v171, v89
	v_exp_f32_e32 v165, v90
	v_exp_f32_e32 v170, v91
	v_exp_f32_e32 v166, v92
	v_exp_f32_e32 v169, v93
	v_exp_f32_e32 v167, v94
	v_exp_f32_e32 v168, v95
	v_fmamk_f32 v228, v64, 0x3e0293ee, v219
	v_fmamk_f32 v229, v65, 0x3e0293ee, v219
	v_fmamk_f32 v230, v66, 0x3e0293ee, v219
	v_fmamk_f32 v231, v67, 0x3e0293ee, v219
	v_fmamk_f32 v232, v68, 0x3e0293ee, v219
	v_fmamk_f32 v221, v69, 0x3e0293ee, v219
	v_fmamk_f32 v222, v70, 0x3e0293ee, v219
	v_fmamk_f32 v223, v71, 0x3e0293ee, v219
	v_fmamk_f32 v224, v72, 0x3e0293ee, v219
	v_fmamk_f32 v225, v73, 0x3e0293ee, v219
	v_fmamk_f32 v226, v74, 0x3e0293ee, v219
	v_fmamk_f32 v227, v75, 0x3e0293ee, v219
	v_fmamk_f32 v220, v76, 0x3e0293ee, v219
	v_fmamk_f32 v233, v77, 0x3e0293ee, v219
	v_fmamk_f32 v234, v78, 0x3e0293ee, v219
	v_fmac_f32_e32 v219, 0x3e0293ee, v79
	s_add_i32 s58, s58, 2
	s_waitcnt lgkmcnt(0)
	s_barrier
	ds_read_b128 v[64:67], v206 offset:32768
	ds_read_b128 v[68:71], v206 offset:40960
	ds_read_b128 v[236:239], v207 offset:32768
	ds_read_b128 v[240:243], v207 offset:40960
	v_exp_f32_e32 v228, v228
	v_exp_f32_e32 v229, v229
	s_waitcnt lgkmcnt(3)
	s_setprio 1
	v_mfma_f32_32x32x16_bf16 v[80:95], v[64:67], v[108:111], 0
	s_setprio 0
	v_exp_f32_e32 v230, v230
	v_exp_f32_e32 v231, v231
	v_exp_f32_e32 v232, v232
	v_exp_f32_e32 v221, v221
	v_exp_f32_e32 v222, v222
	v_exp_f32_e32 v223, v223
	v_exp_f32_e32 v224, v224
	s_waitcnt lgkmcnt(2)
	s_setprio 1
	v_mfma_f32_32x32x16_bf16 v[64:79], v[68:71], v[108:111], 0
	s_setprio 0
	v_exp_f32_e32 v225, v225
	v_exp_f32_e32 v226, v226
	v_exp_f32_e32 v227, v227
	v_exp_f32_e32 v235, v220
	v_exp_f32_e32 v233, v233
	v_exp_f32_e32 v234, v234
	s_waitcnt lgkmcnt(1)
	s_setprio 1
	v_mfma_f32_32x32x16_bf16 v[80:95], v[236:239], v[124:127], v[80:95]
	s_setprio 0
	s_waitcnt lgkmcnt(0)
	s_setprio 1
	v_mfma_f32_32x32x16_bf16 v[64:79], v[240:243], v[124:127], v[64:79]
	s_setprio 0
	ds_read_b128 v[236:239], v208 offset:32768
	ds_read_b128 v[240:243], v208 offset:40960
	s_waitcnt lgkmcnt(1)
	s_setprio 1
	v_mfma_f32_32x32x16_bf16 v[80:95], v[236:239], v[104:107], v[80:95]
	s_setprio 0
	s_waitcnt lgkmcnt(0)
	s_setprio 1
	v_mfma_f32_32x32x16_bf16 v[64:79], v[240:243], v[104:107], v[64:79]
	s_setprio 0
	ds_read_b128 v[236:239], v209 offset:32768
	ds_read_b128 v[240:243], v209 offset:40960
	s_waitcnt lgkmcnt(1)
	s_setprio 1
	v_mfma_f32_32x32x16_bf16 v[80:95], v[236:239], v[120:123], v[80:95]
	s_setprio 0
	s_waitcnt lgkmcnt(0)
	s_setprio 1
	v_mfma_f32_32x32x16_bf16 v[64:79], v[240:243], v[120:123], v[64:79]
	s_setprio 0
	ds_read_b128 v[236:239], v210 offset:32768
	ds_read_b128 v[240:243], v210 offset:40960
	s_waitcnt lgkmcnt(1)
	s_setprio 1
	v_mfma_f32_32x32x16_bf16 v[80:95], v[236:239], v[100:103], v[80:95]
	s_setprio 0
	s_waitcnt lgkmcnt(0)
	s_setprio 1
	v_mfma_f32_32x32x16_bf16 v[64:79], v[240:243], v[100:103], v[64:79]
	s_setprio 0
	ds_read_b128 v[236:239], v211 offset:32768
	ds_read_b128 v[240:243], v211 offset:40960
	s_waitcnt lgkmcnt(1)
	s_setprio 1
	v_mfma_f32_32x32x16_bf16 v[80:95], v[236:239], v[116:119], v[80:95]
	s_setprio 0
	s_waitcnt lgkmcnt(0)
	s_setprio 1
	v_mfma_f32_32x32x16_bf16 v[64:79], v[240:243], v[116:119], v[64:79]
	s_setprio 0
	ds_read_b128 v[236:239], v212 offset:32768
	ds_read_b128 v[240:243], v212 offset:40960
	s_waitcnt lgkmcnt(1)
	s_setprio 1
	v_mfma_f32_32x32x16_bf16 v[80:95], v[236:239], v[96:99], v[80:95]
	s_setprio 0
	s_waitcnt lgkmcnt(0)
	s_setprio 1
	v_mfma_f32_32x32x16_bf16 v[64:79], v[240:243], v[96:99], v[64:79]
	s_setprio 0
	ds_read_b128 v[236:239], v213 offset:32768
	ds_read_b128 v[240:243], v213 offset:40960
	s_waitcnt lgkmcnt(1)
	s_setprio 1
	v_mfma_f32_32x32x16_bf16 v[80:95], v[236:239], v[112:115], v[80:95]
	s_setprio 0
	v_exp_f32_e32 v236, v219
	v_add_f32_e32 v219, 0, v160
	v_add_f32_e32 v219, v175, v219
	v_add_f32_e32 v219, v161, v219
	v_add_f32_e32 v219, v174, v219
	v_add_f32_e32 v219, v162, v219
	v_add_f32_e32 v219, v173, v219
	v_add_f32_e32 v219, v163, v219
	v_add_f32_e32 v219, v172, v219
	v_add_f32_e32 v219, v164, v219
	v_add_f32_e32 v219, v171, v219
	v_add_f32_e32 v219, v165, v219
	v_add_f32_e32 v219, v170, v219
	v_add_f32_e32 v219, v166, v219
	v_add_f32_e32 v219, v169, v219
	v_add_f32_e32 v219, v167, v219
	v_add_f32_e32 v219, v168, v219
	v_add_f32_e32 v219, v228, v219
	v_add_f32_e32 v219, v229, v219
	v_add_f32_e32 v219, v230, v219
	v_add_f32_e32 v219, v231, v219
	v_add_f32_e32 v219, v232, v219
	v_add_f32_e32 v219, v221, v219
	v_add_f32_e32 v219, v222, v219
	v_add_f32_e32 v219, v223, v219
	v_add_f32_e32 v219, v224, v219
	v_add_f32_e32 v219, v225, v219
	s_waitcnt lgkmcnt(0)
	s_setprio 1
	v_mfma_f32_32x32x16_bf16 v[64:79], v[240:243], v[112:115], v[64:79]
	s_setprio 0
	v_add_f32_e32 v219, v226, v219
	v_add_f32_e32 v219, v227, v219
	v_add_f32_e32 v219, v235, v219
	v_add_f32_e32 v219, v233, v219
	v_add_f32_e32 v219, v234, v219
	v_add_f32_e32 v219, v236, v219
	v_mov_b32_e32 v220, v219
	v_cvt_pk_bf16_f32 v160, v160, v175
	v_cvt_pk_bf16_f32 v161, v161, v174
	v_cvt_pk_bf16_f32 v162, v162, v173
	v_cvt_pk_bf16_f32 v163, v163, v172
	v_cvt_pk_bf16_f32 v164, v164, v171
	v_cvt_pk_bf16_f32 v165, v165, v170
	v_cvt_pk_bf16_f32 v166, v166, v169
	v_cvt_pk_bf16_f32 v167, v167, v168
	v_cvt_pk_bf16_f32 v168, v228, v229
	v_cvt_pk_bf16_f32 v169, v230, v231
	v_cvt_pk_bf16_f32 v170, v232, v221
	v_cvt_pk_bf16_f32 v171, v222, v223
	v_cvt_pk_bf16_f32 v172, v224, v225
	v_cvt_pk_bf16_f32 v173, v226, v227
	v_cvt_pk_bf16_f32 v174, v235, v233
	v_cvt_pk_bf16_f32 v175, v234, v236
	s_nop 1
	v_permlane32_swap_b32_e32 v219, v220
	v_permlane32_swap_b32_e32 v160, v162
	v_permlane32_swap_b32_e32 v161, v163
	v_permlane32_swap_b32_e32 v164, v166
	v_permlane32_swap_b32_e32 v165, v167
	v_permlane32_swap_b32_e32 v168, v170
	v_permlane32_swap_b32_e32 v169, v171
	v_permlane32_swap_b32_e32 v172, v174
	v_permlane32_swap_b32_e32 v173, v175
	s_cmp_gt_u32 s58, 28
	s_cselect_b64 s[10:11], -1, 0
	s_and_b64 vcc, exec, s[10:11]
	s_cbranch_vccnz .LBB0_911
; #define SBAR() __builtin_amdgcn_sched_barrier(0)
; #define SLOAD(i, k0) do { sr_[i].vs0 = St::ld8(&Vh[(long)((k0) + sr) * LDK + sc]); sr_[i].vs1 = St::ld8(&Vh[(long)((k0) + 32 + sr) * LDK + sc]); \
;     sr_[i].ks0 = St::ld8(&Kh[(long)((k0) + sr) * LDK + sc]); sr_[i].ks1 = St::ld8(&Kh[(long)((k0) + 32 + sr) * LDK + sc]); } while (0)
; #define SWAIT() do { if constexpr (SDEPTH == 2) asm volatile("s_waitcnt vmcnt(4)" ::: "memory"); else asm volatile("s_waitcnt vmcnt(0)" ::: "memory"); } while (0)
; template <int D0> __device__ __forceinline__ void pv_one(f32x16& od, int vb, bf16x8 pa0, bf16x8 pa1, bf16x8 pa2, bf16x8 pa3) {
;   const s16x4 l0 = tr_read<v_rd_off(D0, 0, 0)>(vb), h0 = tr_read<v_rd_off(D0, 0, 1)>(vb), l1 = tr_read<v_rd_off(D0, 1, 0)>(vb), h1 = tr_read<v_rd_off(D0, 1, 1)>(vb);
;   const s16x4 l2 = tr_read<v_rd_off(D0, 2, 0)>(vb), h2 = tr_read<v_rd_off(D0, 2, 1)>(vb), l3 = tr_read<v_rd_off(D0, 3, 0)>(vb), h3 = tr_read<v_rd_off(D0, 3, 1)>(vb);
;   asm volatile("s_waitcnt lgkmcnt(0)" ::: "memory"); SBAR();
;     ...
;   od = __builtin_amdgcn_mfma_f32_32x32x16_bf16(pa0, PK(l0, h0), od, 0, 0, 0);
;   od = __builtin_amdgcn_mfma_f32_32x32x16_bf16(pa1, PK(l1, h1), od, 0, 0, 0);
;   od = __builtin_amdgcn_mfma_f32_32x32x16_bf16(pa2, PK(l2, h2), od, 0, 0, 0);
;   od = __builtin_amdgcn_mfma_f32_32x32x16_bf16(pa3, PK(l3, h3), od, 0, 0, 0);
;     ...
; }
; __device__ __forceinline__ void pv_d0(f32x16* o, int vb, bf16x8 pa0, bf16x8 pa1, bf16x8 pa2, bf16x8 pa3) {
;   pv_one<0>(o[0], vb, pa0, pa1, pa2, pa3); pv_one<1>(o[1], vb, pa0, pa1, pa2, pa3); pv_one<2>(o[2], vb, pa0, pa1, pa2, pa3); pv_one<3>(o[3], vb, pa0, pa1, pa2, pa3);
; }
; template <typename TQ>
; __device__ __forceinline__ void attn_dense_body(const TQ* __restrict__ Qb, const bf16* __restrict__ Kh, const bf16* __restrict__ Vh,
;                                                 unsigned short* __restrict__ Ob, int seq, char* lds, const float* __restrict__ qg, int pos0) {
;     ...
;     if (SDEPTH == 1 || j + 3 < NT) SLOAD(SE, (j + 1 + SDEPTH) * KVBLK); SBAR();
;     pv_d0(o, vb0 + (int)SHM_V, pa0, pa1, pa2, pa3); partialSM(pA0, pA1, m_reg, mnA, alA);
;     __syncthreads(); SWAIT(); SWRITE(1, SO);
;     RESC(alA); __syncthreads();
	v_add_co_u32_e32 v132, vcc, 0xfffc8000, v186
	s_nop 1
	v_addc_co_u32_e32 v133, vcc, -1, v187, vcc
	global_load_dwordx4 v[128:131], v[132:133], off
	s_nop 0
	global_load_dwordx4 v[132:135], v[132:133], off offset:-512
	s_nop 0
	global_load_dwordx4 v[136:139], v[186:187], off
	global_load_dwordx4 v[140:143], v[186:187], off offset:-512
.LBB0_911:
	ds_read_b64_tr_b16 v[222:223], v200 offset:0
	ds_read_b64_tr_b16 v[224:225], v200 offset:0x800
	ds_read_b64_tr_b16 v[226:227], v200 offset:0x1000
	ds_read_b64_tr_b16 v[228:229], v200 offset:0x1800
	ds_read_b64_tr_b16 v[230:231], v200 offset:0x2000
	ds_read_b64_tr_b16 v[232:233], v200 offset:0x2800
	ds_read_b64_tr_b16 v[234:235], v200 offset:0x3000
	ds_read_b64_tr_b16 v[236:237], v200 offset:0x3800
	s_waitcnt lgkmcnt(0)
	s_nop 0
	s_setprio 1
	v_mfma_f32_32x32x16_bf16 v[0:15], v[160:163], v[222:225], v[0:15]
	s_setprio 0
	ds_read_b64_tr_b16 v[222:223], v200 offset:0x200
	ds_read_b64_tr_b16 v[224:225], v200 offset:0xa00
	s_setprio 1
	v_mfma_f32_32x32x16_bf16 v[0:15], v[164:167], v[226:229], v[0:15]
	s_setprio 0
	ds_read_b64_tr_b16 v[226:227], v200 offset:0x1200
	ds_read_b64_tr_b16 v[228:229], v200 offset:0x1a00
	s_setprio 1
	v_mfma_f32_32x32x16_bf16 v[0:15], v[168:171], v[230:233], v[0:15]
	s_setprio 0
	ds_read_b64_tr_b16 v[230:231], v200 offset:0x2200
	ds_read_b64_tr_b16 v[232:233], v200 offset:0x2a00
	ds_read_b64_tr_b16 v[238:239], v200 offset:0x3200
	ds_read_b64_tr_b16 v[240:241], v200 offset:0x3a00
	s_waitcnt lgkmcnt(0)
	s_setprio 1
	v_mfma_f32_32x32x16_bf16 v[0:15], v[172:175], v[234:237], v[0:15]
	v_mfma_f32_32x32x16_bf16 v[48:63], v[160:163], v[222:225], v[48:63]
	s_setprio 0
	ds_read_b64_tr_b16 v[222:223], v200 offset:0x400
	ds_read_b64_tr_b16 v[224:225], v200 offset:0xc00
	s_setprio 1
	v_mfma_f32_32x32x16_bf16 v[48:63], v[164:167], v[226:229], v[48:63]
	s_setprio 0
	ds_read_b64_tr_b16 v[226:227], v200 offset:0x1400
	ds_read_b64_tr_b16 v[228:229], v200 offset:0x1c00
	s_setprio 1
	v_mfma_f32_32x32x16_bf16 v[48:63], v[168:171], v[230:233], v[48:63]
	s_setprio 0
	ds_read_b64_tr_b16 v[230:231], v200 offset:0x2400
	ds_read_b64_tr_b16 v[232:233], v200 offset:0x2c00
	ds_read_b64_tr_b16 v[234:235], v200 offset:0x3400
	ds_read_b64_tr_b16 v[236:237], v200 offset:0x3c00
	s_waitcnt lgkmcnt(0)
	s_setprio 1
	v_mfma_f32_32x32x16_bf16 v[48:63], v[172:175], v[238:241], v[48:63]
	v_mfma_f32_32x32x16_bf16 v[32:47], v[160:163], v[222:225], v[32:47]
	s_setprio 0
	ds_read_b64_tr_b16 v[222:223], v200 offset:0x600
	ds_read_b64_tr_b16 v[224:225], v200 offset:0xe00
	s_setprio 1
	v_mfma_f32_32x32x16_bf16 v[32:47], v[164:167], v[226:229], v[32:47]
	s_setprio 0
	ds_read_b64_tr_b16 v[226:227], v200 offset:0x1600
	ds_read_b64_tr_b16 v[228:229], v200 offset:0x1e00
	s_setprio 1
	v_mfma_f32_32x32x16_bf16 v[32:47], v[168:171], v[230:233], v[32:47]
	s_setprio 0
	ds_read_b64_tr_b16 v[230:231], v200 offset:0x2600
	ds_read_b64_tr_b16 v[232:233], v200 offset:0x2e00
	ds_read_b64_tr_b16 v[238:239], v200 offset:0x3600
	ds_read_b64_tr_b16 v[240:241], v200 offset:0x3e00
	s_waitcnt lgkmcnt(0)
	s_setprio 1
	v_mfma_f32_32x32x16_bf16 v[32:47], v[172:175], v[234:237], v[32:47]
	v_mfma_f32_32x32x16_bf16 v[16:31], v[160:163], v[222:225], v[16:31]
	s_setprio 0
	v_max_f32_e32 v221, v81, v81
	v_max_f32_e32 v234, v80, v80
	v_max_f32_e32 v221, v234, v221
	v_max3_f32 v221, v221, v82, v83
	v_max3_f32 v221, v221, v84, v85
	v_max3_f32 v160, v221, v86, v87
	v_max3_f32 v160, v160, v88, v89
	v_max3_f32 v160, v160, v90, v91
	s_setprio 1
	v_mfma_f32_32x32x16_bf16 v[16:31], v[164:167], v[226:229], v[16:31]
	s_setprio 0
	v_max3_f32 v160, v160, v92, v93
	v_max3_f32 v160, v160, v94, v95
	v_max3_f32 v160, v160, v64, v65
	v_max3_f32 v160, v160, v66, v67
	v_max3_f32 v160, v160, v68, v69
	v_max3_f32 v160, v160, v70, v71
	v_max3_f32 v160, v160, v72, v73
	v_max3_f32 v160, v160, v74, v75
	s_setprio 1
	v_mfma_f32_32x32x16_bf16 v[16:31], v[168:171], v[230:233], v[16:31]
	s_setprio 0
	v_max3_f32 v160, v160, v76, v77
	v_max3_f32 v160, v160, v78, v79
	v_mov_b32_e32 v161, v160
	s_nop 1
	v_permlane32_swap_b32_e32 v160, v161
	v_max_f32_e32 v161, v161, v161
	v_max_f32_e32 v160, v160, v160
	v_max_f32_e32 v160, v160, v161
	v_max_f32_e32 v162, v218, v218
	v_sub_f32_e32 v161, v160, v218
	v_max_f32_e32 v160, v162, v160
	s_setprio 1
	v_mfma_f32_32x32x16_bf16 v[16:31], v[172:175], v[238:241], v[16:31]
	s_setprio 0
	v_sub_f32_e32 v162, v218, v160
	v_mul_f32_e32 v162, 0x3e0293ee, v162
	v_exp_f32_e32 v162, v162
	v_cmp_ge_f32_e32 vcc, s45, v161
	s_cmp_eq_u64 vcc, exec
	s_cselect_b64 s[6:7], -1, 0
	s_barrier
	s_waitcnt vmcnt(4)
	v_cndmask_b32_e64 v161, v162, 1.0, s[6:7]
	v_cmp_gt_f32_e32 vcc, 1.0, v161
	s_waitcnt vmcnt(3)
	ds_write_b128 v202, v[144:147] offset:16384
	s_waitcnt vmcnt(1)
	ds_write_b128 v203, v[156:159] offset:16384
	ds_write_b128 v204, v[148:151] offset:49152
	s_waitcnt vmcnt(0)
	ds_write_b128 v205, v[152:155] offset:49152
	s_cbranch_vccz .LBB0_915
	s_and_saveexec_b64 s[12:13], s[4:5]
	ds_write_b32 v198, v161 offset:128
	s_or_b64 exec, exec, s[12:13]
	s_waitcnt lgkmcnt(0)
	v_add_u32_e32 v156, v185, v182
	ds_read_b128 v[144:147], v156 offset:224
	ds_read_b128 v[148:151], v156 offset:192
	ds_read_b128 v[152:155], v156 offset:160
	ds_read_b128 v[156:159], v156 offset:128
	s_waitcnt lgkmcnt(3)
	v_pk_mul_f32 v[12:13], v[12:13], v[144:145]
	s_waitcnt lgkmcnt(2)
	v_pk_mul_f32 v[8:9], v[8:9], v[148:149]
	s_waitcnt lgkmcnt(1)
	v_pk_mul_f32 v[4:5], v[4:5], v[152:153]
	v_pk_mul_f32 v[14:15], v[14:15], v[146:147]
	v_pk_mul_f32 v[10:11], v[10:11], v[150:151]
	v_pk_mul_f32 v[6:7], v[6:7], v[154:155]
	s_waitcnt lgkmcnt(0)
	v_pk_mul_f32 v[2:3], v[2:3], v[158:159]
	v_pk_mul_f32 v[0:1], v[0:1], v[156:157]
	v_pk_mul_f32 v[60:61], v[60:61], v[144:145]
	v_pk_mul_f32 v[56:57], v[56:57], v[148:149]
	v_pk_mul_f32 v[52:53], v[52:53], v[152:153]
	v_pk_mul_f32 v[62:63], v[62:63], v[146:147]
	v_pk_mul_f32 v[58:59], v[58:59], v[150:151]
	v_pk_mul_f32 v[54:55], v[54:55], v[154:155]
	v_pk_mul_f32 v[50:51], v[50:51], v[158:159]
	v_pk_mul_f32 v[48:49], v[48:49], v[156:157]
	v_pk_mul_f32 v[44:45], v[44:45], v[144:145]
	v_pk_mul_f32 v[40:41], v[40:41], v[148:149]
	v_pk_mul_f32 v[36:37], v[36:37], v[152:153]
	v_pk_mul_f32 v[46:47], v[46:47], v[146:147]
	v_pk_mul_f32 v[42:43], v[42:43], v[150:151]
	v_pk_mul_f32 v[38:39], v[38:39], v[154:155]
	v_pk_mul_f32 v[34:35], v[34:35], v[158:159]
	v_pk_mul_f32 v[32:33], v[32:33], v[156:157]
	v_pk_mul_f32 v[28:29], v[28:29], v[144:145]
	v_pk_mul_f32 v[24:25], v[24:25], v[148:149]
	v_pk_mul_f32 v[20:21], v[20:21], v[152:153]
	v_pk_mul_f32 v[30:31], v[30:31], v[146:147]
	v_pk_mul_f32 v[26:27], v[26:27], v[150:151]
	v_pk_mul_f32 v[22:23], v[22:23], v[154:155]
	v_pk_mul_f32 v[18:19], v[18:19], v[158:159]
	v_pk_mul_f32 v[16:17], v[16:17], v[156:157]

; #define SBAR() __builtin_amdgcn_sched_barrier(0)
; __device__ __forceinline__ void finishSM(f32x16& p0, f32x16& p1, float alpha, float& l_reg, bf16x8& pa0, bf16x8& pa1, bf16x8& pa2, bf16x8& pa3) {
;   for (int r = 0; r < 16; ++r) p1[r] = __builtin_amdgcn_exp2f(p1[r]);
;   float ps = 0; for (int r = 0; r < 16; ++r) ps += p0[r]; for (int r = 0; r < 16; ++r) ps += p1[r];
;   { auto rr = __builtin_amdgcn_permlane32_swap(__float_as_uint(ps), __float_as_uint(ps), false, false);
;     ps = __uint_as_float(rr[0]) + __uint_as_float(rr[1]); }
;   l_reg = l_reg * alpha + ps;
;     ...
;   PK4(p0, 0, pa0); PK4(p0, 8, pa1); PK4(p1, 0, pa2); PK4(p1, 8, pa3);
;     ...
; }
; __device__ __forceinline__ void qkt(f32x16& p0, f32x16& p1, const bf16* Ks, const bf16x8* qr, int r32, int hi) {
;   p0 = f32x16{}; p1 = f32x16{};
;   for (int d0 = 0; d0 < 8; ++d0) { int cb = (d0 * 16 + hi * 8) * 2;
;     bf16x8 b0 = *reinterpret_cast<const bf16x8*>((const char*)Ks + KSWZ(r32, cb));
;     bf16x8 b1 = *reinterpret_cast<const bf16x8*>((const char*)Ks + KSWZ(32 + r32, cb));
;     p0 = __builtin_amdgcn_mfma_f32_32x32x16_bf16(b0, qr[d0], p0, 0, 0, 0);
;     p1 = __builtin_amdgcn_mfma_f32_32x32x16_bf16(b1, qr[d0], p1, 0, 0, 0); }
; template <typename TQ>
; __device__ __forceinline__ void attn_dense_body(const TQ* __restrict__ Qb, const bf16* __restrict__ Kh, const bf16* __restrict__ Vh,
;                                                 unsigned short* __restrict__ Ob, int seq, char* lds, const float* __restrict__ qg, int pos0) {
;     ...
;   SBAR(); qkt(pB0, pB1, (bf16*)((char*)K_lds + SHM_K), qr, r32, hi);
;   finishSM(pA0, pA1, alA, l_reg, pa0, pa1, pa2, pa3); SBAR();
.LBB0_917:
	ds_read_b128 v[64:67], v206 offset:49152
	ds_read_b128 v[68:71], v206 offset:57344
	v_exp_f32_e32 v154, v154
	v_exp_f32_e32 v155, v155
	v_exp_f32_e32 v152, v152
	s_waitcnt lgkmcnt(1)
	s_setprio 1
	v_mfma_f32_32x32x16_bf16 v[80:95], v[64:67], v[108:111], 0
	s_setprio 0
	v_exp_f32_e32 v153, v153
	v_exp_f32_e32 v148, v148
	s_waitcnt lgkmcnt(0)
	s_setprio 1
	v_mfma_f32_32x32x16_bf16 v[64:79], v[68:71], v[108:111], 0
	s_setprio 0
	ds_read_b128 v[108:111], v207 offset:49152
	ds_read_b128 v[128:131], v207 offset:57344
	ds_read_b128 v[132:135], v208 offset:49152
	ds_read_b128 v[136:139], v208 offset:57344
	s_waitcnt lgkmcnt(3)
	s_setprio 1
	v_mfma_f32_32x32x16_bf16 v[80:95], v[108:111], v[124:127], v[80:95]
	s_setprio 0
	ds_read_b128 v[108:111], v209 offset:49152
	ds_read_b128 v[140:143], v209 offset:57344
	ds_read_b128 v[202:205], v210 offset:49152
	ds_read_b128 v[206:209], v210 offset:57344
	ds_read_b128 v[214:217], v211 offset:49152
	ds_read_b128 v[222:225], v211 offset:57344
	ds_read_b128 v[226:229], v212 offset:49152
	ds_read_b128 v[230:233], v212 offset:57344
	s_waitcnt lgkmcnt(10)
	s_setprio 1
	v_mfma_f32_32x32x16_bf16 v[64:79], v[128:131], v[124:127], v[64:79]
	s_setprio 0
	ds_read_b128 v[124:127], v213 offset:49152
	ds_read_b128 v[128:131], v213 offset:57344
	s_waitcnt lgkmcnt(11)
	s_setprio 1
	v_mfma_f32_32x32x16_bf16 v[80:95], v[132:135], v[104:107], v[80:95]
	s_setprio 0
	v_exp_f32_e32 v132, v149
	v_exp_f32_e32 v133, v146
	v_exp_f32_e32 v134, v147
	v_exp_f32_e32 v135, v144
	v_exp_f32_e32 v144, v145
	v_exp_f32_e32 v145, v158
	v_exp_f32_e32 v146, v159
	s_waitcnt lgkmcnt(10)
	s_setprio 1
	v_mfma_f32_32x32x16_bf16 v[64:79], v[136:139], v[104:107], v[64:79]
	s_setprio 0
	v_add_f32_e32 v104, 0, v175
	v_add_f32_e32 v104, v221, v104
	v_add_f32_e32 v104, v173, v104
	v_add_f32_e32 v104, v218, v104
	v_add_f32_e32 v104, v172, v104
	v_add_f32_e32 v104, v174, v104
	v_add_f32_e32 v104, v170, v104
	s_waitcnt lgkmcnt(9)
	s_setprio 1
	v_mfma_f32_32x32x16_bf16 v[80:95], v[108:111], v[120:123], v[80:95]
	s_setprio 0
	v_add_f32_e32 v104, v171, v104
	v_add_f32_e32 v104, v167, v104
	v_add_f32_e32 v104, v169, v104
	v_add_f32_e32 v104, v166, v104
	v_add_f32_e32 v104, v168, v104
	v_add_f32_e32 v104, v163, v104
	v_add_f32_e32 v104, v165, v104
	s_waitcnt lgkmcnt(8)
	s_setprio 1
	v_mfma_f32_32x32x16_bf16 v[64:79], v[140:143], v[120:123], v[64:79]
	s_setprio 0
	v_add_f32_e32 v104, v162, v104
	v_add_f32_e32 v104, v164, v104
	v_add_f32_e32 v104, v154, v104
	v_add_f32_e32 v104, v155, v104
	v_add_f32_e32 v104, v152, v104
	v_add_f32_e32 v104, v153, v104
	v_add_f32_e32 v104, v148, v104
	s_waitcnt lgkmcnt(7)
	s_setprio 1
	v_mfma_f32_32x32x16_bf16 v[80:95], v[202:205], v[100:103], v[80:95]
	s_setprio 0
	v_add_f32_e32 v104, v132, v104
	v_add_f32_e32 v104, v133, v104
	v_add_f32_e32 v104, v134, v104
	v_exp_f32_e32 v136, v156
	v_exp_f32_e32 v137, v157
	v_exp_f32_e32 v138, v150
	v_exp_f32_e32 v139, v151
	s_waitcnt lgkmcnt(6)
	s_setprio 1
	v_mfma_f32_32x32x16_bf16 v[64:79], v[206:209], v[100:103], v[64:79]
	s_setprio 0
	v_add_f32_e32 v100, v135, v104
	v_add_f32_e32 v100, v144, v100
	v_add_f32_e32 v100, v145, v100
	v_add_f32_e32 v100, v146, v100
	v_add_f32_e32 v100, v136, v100
	v_add_f32_e32 v100, v137, v100
	v_add_f32_e32 v100, v138, v100
	s_waitcnt lgkmcnt(5)
	s_setprio 1
	v_mfma_f32_32x32x16_bf16 v[80:95], v[214:217], v[116:119], v[80:95]
	s_setprio 0
	v_add_f32_e32 v100, v139, v100
	v_mov_b32_e32 v101, v100
	s_nop 1
	v_permlane32_swap_b32_e32 v100, v101
	v_cvt_pk_bf16_f32 v102, v175, v221
	v_cvt_pk_bf16_f32 v103, v173, v218
	v_cvt_pk_bf16_f32 v104, v172, v174
	s_waitcnt lgkmcnt(4)
	s_setprio 1
	v_mfma_f32_32x32x16_bf16 v[64:79], v[222:225], v[116:119], v[64:79]
	s_setprio 0
	v_cvt_pk_bf16_f32 v105, v170, v171
	v_cvt_pk_bf16_f32 v106, v167, v169
	v_cvt_pk_bf16_f32 v107, v166, v168
	v_cvt_pk_bf16_f32 v108, v163, v165
	v_cvt_pk_bf16_f32 v109, v162, v164
	v_cvt_pk_bf16_f32 v116, v154, v155
	v_cvt_pk_bf16_f32 v117, v152, v153
	s_waitcnt lgkmcnt(3)
	s_setprio 1
	v_mfma_f32_32x32x16_bf16 v[80:95], v[226:229], v[96:99], v[80:95]
	s_setprio 0
	v_cvt_pk_bf16_f32 v118, v148, v132
	v_cvt_pk_bf16_f32 v119, v133, v134
	v_cvt_pk_bf16_f32 v120, v135, v144
	v_cvt_pk_bf16_f32 v121, v145, v146
	v_cvt_pk_bf16_f32 v122, v136, v137
	v_cvt_pk_bf16_f32 v123, v138, v139
	v_permlane32_swap_b32_e32 v102, v104
	s_waitcnt lgkmcnt(2)
	s_setprio 1
	v_mfma_f32_32x32x16_bf16 v[64:79], v[230:233], v[96:99], v[64:79]
	s_setprio 0
	v_permlane32_swap_b32_e32 v103, v105
	v_permlane32_swap_b32_e32 v106, v108
	v_permlane32_swap_b32_e32 v107, v109
	v_permlane32_swap_b32_e32 v116, v118
	s_waitcnt lgkmcnt(1)
	s_setprio 1
	v_mfma_f32_32x32x16_bf16 v[80:95], v[124:127], v[112:115], v[80:95]
	s_setprio 0
	v_permlane32_swap_b32_e32 v117, v119
	v_permlane32_swap_b32_e32 v120, v122
	v_permlane32_swap_b32_e32 v121, v123
	s_waitcnt lgkmcnt(0)
	s_setprio 1
	v_mfma_f32_32x32x16_bf16 v[64:79], v[128:131], v[112:115], v[64:79]
	s_setprio 0
	ds_read_b64_tr_b16 v[96:97], v201 offset:0
	ds_read_b64_tr_b16 v[98:99], v201 offset:0x800
	ds_read_b64_tr_b16 v[110:111], v201 offset:0x1000
	ds_read_b64_tr_b16 v[112:113], v201 offset:0x1800
	ds_read_b64_tr_b16 v[124:125], v201 offset:0x2000
	ds_read_b64_tr_b16 v[126:127], v201 offset:0x2800
	ds_read_b64_tr_b16 v[128:129], v201 offset:0x3000
	ds_read_b64_tr_b16 v[130:131], v201 offset:0x3800
	s_waitcnt lgkmcnt(0)
; #define SBAR() __builtin_amdgcn_sched_barrier(0)
; #define RESC(a) do { if (__any((a) < 1.f)) { if (hi == 0) al_l[r32] = (a); asm volatile("s_waitcnt lgkmcnt(0)" ::: "memory"); \
;     for (int d = 0; d < 4; ++d) for (int r = 0; r < 16; ++r) o[d][r] *= al_l[crow(r, hi)]; } } while (0)
; template <int D0> __device__ __forceinline__ void pv_one(f32x16& od, int vb, bf16x8 pa0, bf16x8 pa1, bf16x8 pa2, bf16x8 pa3) {
;   const s16x4 l0 = tr_read<v_rd_off(D0, 0, 0)>(vb), h0 = tr_read<v_rd_off(D0, 0, 1)>(vb), l1 = tr_read<v_rd_off(D0, 1, 0)>(vb), h1 = tr_read<v_rd_off(D0, 1, 1)>(vb);
;   const s16x4 l2 = tr_read<v_rd_off(D0, 2, 0)>(vb), h2 = tr_read<v_rd_off(D0, 2, 1)>(vb), l3 = tr_read<v_rd_off(D0, 3, 0)>(vb), h3 = tr_read<v_rd_off(D0, 3, 1)>(vb);
;   asm volatile("s_waitcnt lgkmcnt(0)" ::: "memory"); SBAR();
;     ...
;   od = __builtin_amdgcn_mfma_f32_32x32x16_bf16(pa0, PK(l0, h0), od, 0, 0, 0);
;   od = __builtin_amdgcn_mfma_f32_32x32x16_bf16(pa1, PK(l1, h1), od, 0, 0, 0);
;   od = __builtin_amdgcn_mfma_f32_32x32x16_bf16(pa2, PK(l2, h2), od, 0, 0, 0);
;   od = __builtin_amdgcn_mfma_f32_32x32x16_bf16(pa3, PK(l3, h3), od, 0, 0, 0);
;     ...
; }
; __device__ __forceinline__ void pv_d0(f32x16* o, int vb, bf16x8 pa0, bf16x8 pa1, bf16x8 pa2, bf16x8 pa3) {
;   pv_one<0>(o[0], vb, pa0, pa1, pa2, pa3); pv_one<1>(o[1], vb, pa0, pa1, pa2, pa3); pv_one<2>(o[2], vb, pa0, pa1, pa2, pa3); pv_one<3>(o[3], vb, pa0, pa1, pa2, pa3);
; }
; template <typename TQ>
; __device__ __forceinline__ void attn_dense_body(const TQ* __restrict__ Qb, const bf16* __restrict__ Kh, const bf16* __restrict__ Vh,
;                                                 unsigned short* __restrict__ Ob, int seq, char* lds, const float* __restrict__ qg, int pos0) {
;     ...
;   pv_d0(o, vb0, pa0, pa1, pa2, pa3); partialSM(pB0, pB1, m_reg, mnB, alB);
;   __syncthreads(); RESC(alB);
	s_nop 0
	s_setprio 1
	v_mfma_f32_32x32x16_bf16 v[0:15], v[102:105], v[96:99], v[0:15]
	s_setprio 0
	ds_read_b64_tr_b16 v[96:97], v201 offset:0x200
	ds_read_b64_tr_b16 v[98:99], v201 offset:0xa00
	s_setprio 1
	v_mfma_f32_32x32x16_bf16 v[0:15], v[106:109], v[110:113], v[0:15]
	s_setprio 0
	ds_read_b64_tr_b16 v[110:111], v201 offset:0x1200
	ds_read_b64_tr_b16 v[112:113], v201 offset:0x1a00
	s_setprio 1
	v_mfma_f32_32x32x16_bf16 v[0:15], v[116:119], v[124:127], v[0:15]
	s_setprio 0
	ds_read_b64_tr_b16 v[124:125], v201 offset:0x2200
	ds_read_b64_tr_b16 v[126:127], v201 offset:0x2a00
	ds_read_b64_tr_b16 v[132:133], v201 offset:0x3200
	ds_read_b64_tr_b16 v[134:135], v201 offset:0x3a00
	s_waitcnt lgkmcnt(0)
	s_setprio 1
	v_mfma_f32_32x32x16_bf16 v[0:15], v[120:123], v[128:131], v[0:15]
	v_mfma_f32_32x32x16_bf16 v[48:63], v[102:105], v[96:99], v[48:63]
	s_setprio 0
	ds_read_b64_tr_b16 v[96:97], v201 offset:0x400
	ds_read_b64_tr_b16 v[98:99], v201 offset:0xc00
	s_setprio 1
	v_mfma_f32_32x32x16_bf16 v[48:63], v[106:109], v[110:113], v[48:63]
	s_setprio 0
	ds_read_b64_tr_b16 v[110:111], v201 offset:0x1400
	ds_read_b64_tr_b16 v[112:113], v201 offset:0x1c00
	s_setprio 1
	v_mfma_f32_32x32x16_bf16 v[48:63], v[116:119], v[124:127], v[48:63]
	s_setprio 0
	ds_read_b64_tr_b16 v[124:125], v201 offset:0x2400
	ds_read_b64_tr_b16 v[126:127], v201 offset:0x2c00
	ds_read_b64_tr_b16 v[128:129], v201 offset:0x3400
	ds_read_b64_tr_b16 v[130:131], v201 offset:0x3c00
	s_waitcnt lgkmcnt(0)
	s_setprio 1
	v_mfma_f32_32x32x16_bf16 v[48:63], v[120:123], v[132:135], v[48:63]
	v_mfma_f32_32x32x16_bf16 v[32:47], v[102:105], v[96:99], v[32:47]
	s_setprio 0
	ds_read_b64_tr_b16 v[96:97], v201 offset:0x600
	ds_read_b64_tr_b16 v[98:99], v201 offset:0xe00
	s_setprio 1
	v_mfma_f32_32x32x16_bf16 v[32:47], v[106:109], v[110:113], v[32:47]
	s_setprio 0
	ds_read_b64_tr_b16 v[110:111], v201 offset:0x1600
	ds_read_b64_tr_b16 v[112:113], v201 offset:0x1e00
	s_setprio 1
	v_mfma_f32_32x32x16_bf16 v[32:47], v[116:119], v[124:127], v[32:47]
	s_setprio 0
	ds_read_b64_tr_b16 v[124:125], v201 offset:0x2600
	ds_read_b64_tr_b16 v[126:127], v201 offset:0x2e00
	ds_read_b64_tr_b16 v[132:133], v201 offset:0x3600
	ds_read_b64_tr_b16 v[134:135], v201 offset:0x3e00
	s_waitcnt lgkmcnt(0)
	s_setprio 1
	v_mfma_f32_32x32x16_bf16 v[32:47], v[120:123], v[128:131], v[32:47]
	v_mfma_f32_32x32x16_bf16 v[16:31], v[102:105], v[96:99], v[16:31]
	s_setprio 0
	v_max_f32_e32 v114, v81, v81
	v_max_f32_e32 v115, v80, v80
	v_max_f32_e32 v114, v115, v114
	v_max3_f32 v114, v114, v82, v83
	v_max3_f32 v114, v114, v84, v85
	v_max3_f32 v96, v114, v86, v87
	v_max3_f32 v96, v96, v88, v89
	v_max3_f32 v96, v96, v90, v91
	s_setprio 1
	v_mfma_f32_32x32x16_bf16 v[16:31], v[106:109], v[110:113], v[16:31]
	s_setprio 0
	v_max3_f32 v96, v96, v92, v93
	v_max3_f32 v96, v96, v94, v95
	v_max3_f32 v96, v96, v64, v65
	v_max3_f32 v96, v96, v66, v67
	v_max3_f32 v96, v96, v68, v69
	v_max3_f32 v96, v96, v70, v71
	v_max3_f32 v96, v96, v72, v73
	v_max3_f32 v96, v96, v74, v75
	s_setprio 1
	v_mfma_f32_32x32x16_bf16 v[16:31], v[116:119], v[124:127], v[16:31]
	s_setprio 0
	v_max3_f32 v96, v96, v76, v77
	v_max3_f32 v96, v96, v78, v79
	v_mov_b32_e32 v97, v96
	s_nop 1
	v_permlane32_swap_b32_e32 v96, v97
	v_max_f32_e32 v97, v97, v97
	v_max_f32_e32 v96, v96, v96
	v_max_f32_e32 v96, v96, v97
	v_max_f32_e32 v97, v160, v160
	v_max_f32_e32 v97, v97, v96
	v_sub_f32_e32 v98, v96, v160
	s_setprio 1
	v_mfma_f32_32x32x16_bf16 v[16:31], v[120:123], v[132:135], v[16:31]
	s_setprio 0
	v_sub_f32_e32 v96, v160, v97
	v_mul_f32_e32 v96, 0x3e0293ee, v96
	v_exp_f32_e32 v96, v96
	v_cmp_ge_f32_e32 vcc, s45, v98
	s_cmp_eq_u64 vcc, exec
	s_cselect_b64 s[6:7], -1, 0
	v_cndmask_b32_e64 v96, v96, 1.0, s[6:7]
	v_cmp_gt_f32_e32 vcc, 1.0, v96
	s_barrier
	s_cbranch_vccz .LBB0_921
	s_and_saveexec_b64 s[10:11], s[4:5]
	ds_write_b32 v198, v96 offset:128
	s_or_b64 exec, exec, s[10:11]
	s_waitcnt lgkmcnt(0)
	v_add_u32_e32 v98, v185, v182
	ds_read_b128 v[102:105], v98 offset:224
	ds_read_b128 v[106:109], v98 offset:192
	ds_read_b128 v[110:113], v98 offset:160
	ds_read_b128 v[114:117], v98 offset:128
	s_waitcnt lgkmcnt(3)
	v_pk_mul_f32 v[12:13], v[12:13], v[102:103]
	s_waitcnt lgkmcnt(2)
	v_pk_mul_f32 v[8:9], v[8:9], v[106:107]
	s_waitcnt lgkmcnt(1)
	v_pk_mul_f32 v[4:5], v[4:5], v[110:111]
	v_pk_mul_f32 v[14:15], v[14:15], v[104:105]
	v_pk_mul_f32 v[10:11], v[10:11], v[108:109]
	v_pk_mul_f32 v[6:7], v[6:7], v[112:113]
	s_waitcnt lgkmcnt(0)
	v_pk_mul_f32 v[2:3], v[2:3], v[116:117]
	v_pk_mul_f32 v[0:1], v[0:1], v[114:115]
	v_pk_mul_f32 v[60:61], v[60:61], v[102:103]
	v_pk_mul_f32 v[56:57], v[56:57], v[106:107]
	v_pk_mul_f32 v[52:53], v[52:53], v[110:111]
	v_pk_mul_f32 v[62:63], v[62:63], v[104:105]
	v_pk_mul_f32 v[58:59], v[58:59], v[108:109]
	v_pk_mul_f32 v[54:55], v[54:55], v[112:113]
	v_pk_mul_f32 v[50:51], v[50:51], v[116:117]
	v_pk_mul_f32 v[48:49], v[48:49], v[114:115]
	v_pk_mul_f32 v[44:45], v[44:45], v[102:103]
	v_pk_mul_f32 v[40:41], v[40:41], v[106:107]
	v_pk_mul_f32 v[36:37], v[36:37], v[110:111]
	v_pk_mul_f32 v[46:47], v[46:47], v[104:105]
	v_pk_mul_f32 v[42:43], v[42:43], v[108:109]
	v_pk_mul_f32 v[38:39], v[38:39], v[112:113]
	v_pk_mul_f32 v[34:35], v[34:35], v[116:117]
	v_pk_mul_f32 v[32:33], v[32:33], v[114:115]
	v_pk_mul_f32 v[28:29], v[28:29], v[102:103]
	v_pk_mul_f32 v[24:25], v[24:25], v[106:107]
	v_pk_mul_f32 v[20:21], v[20:21], v[110:111]
	v_pk_mul_f32 v[30:31], v[30:31], v[104:105]
	v_pk_mul_f32 v[26:27], v[26:27], v[108:109]
	v_pk_mul_f32 v[22:23], v[22:23], v[112:113]
	v_pk_mul_f32 v[18:19], v[18:19], v[116:117]
	v_pk_mul_f32 v[16:17], v[16:17], v[114:115]
; #define SBAR() __builtin_amdgcn_sched_barrier(0)
; __device__ __forceinline__ void partialSM(f32x16& p0, f32x16& p1, float& m_reg, float& mn, float& alpha) {
;     ...
;   for (int r = 0; r < 16; ++r) p0[r] = fmaf(p0[r], C, mnC); for (int r = 0; r < 16; ++r) p1[r] = fmaf(p1[r], C, mnC);
;   for (int r = 0; r < 16; ++r) p0[r] = __builtin_amdgcn_exp2f(p0[r]);
; }
; __device__ __forceinline__ void finishSM(f32x16& p0, f32x16& p1, float alpha, float& l_reg, bf16x8& pa0, bf16x8& pa1, bf16x8& pa2, bf16x8& pa3) {
;   for (int r = 0; r < 16; ++r) p1[r] = __builtin_amdgcn_exp2f(p1[r]);
;   float ps = 0; for (int r = 0; r < 16; ++r) ps += p0[r]; for (int r = 0; r < 16; ++r) ps += p1[r];
;   { auto rr = __builtin_amdgcn_permlane32_swap(__float_as_uint(ps), __float_as_uint(ps), false, false);
;     ps = __uint_as_float(rr[0]) + __uint_as_float(rr[1]); }
;   l_reg = l_reg * alpha + ps;
;     ...
;   PK4(p0, 0, pa0); PK4(p0, 8, pa1); PK4(p1, 0, pa2); PK4(p1, 8, pa3);
; template <int D0> __device__ __forceinline__ void pv_one(f32x16& od, int vb, bf16x8 pa0, bf16x8 pa1, bf16x8 pa2, bf16x8 pa3) {
;   const s16x4 l0 = tr_read<v_rd_off(D0, 0, 0)>(vb), h0 = tr_read<v_rd_off(D0, 0, 1)>(vb), l1 = tr_read<v_rd_off(D0, 1, 0)>(vb), h1 = tr_read<v_rd_off(D0, 1, 1)>(vb);
;   const s16x4 l2 = tr_read<v_rd_off(D0, 2, 0)>(vb), h2 = tr_read<v_rd_off(D0, 2, 1)>(vb), l3 = tr_read<v_rd_off(D0, 3, 0)>(vb), h3 = tr_read<v_rd_off(D0, 3, 1)>(vb);
;   asm volatile("s_waitcnt lgkmcnt(0)" ::: "memory"); SBAR();
;     ...
;   od = __builtin_amdgcn_mfma_f32_32x32x16_bf16(pa0, PK(l0, h0), od, 0, 0, 0);
;   od = __builtin_amdgcn_mfma_f32_32x32x16_bf16(pa1, PK(l1, h1), od, 0, 0, 0);
;   od = __builtin_amdgcn_mfma_f32_32x32x16_bf16(pa2, PK(l2, h2), od, 0, 0, 0);
;   od = __builtin_amdgcn_mfma_f32_32x32x16_bf16(pa3, PK(l3, h3), od, 0, 0, 0);
.LBB0_921:
	v_cndmask_b32_e64 v97, v97, v160, s[6:7]
	v_mul_f32_e32 v97, 0xbe0293ee, v97
	v_fmamk_f32 v80, v80, 0x3e0293ee, v97
	v_fmamk_f32 v81, v81, 0x3e0293ee, v97
	v_fmamk_f32 v98, v82, 0x3e0293ee, v97
	v_exp_f32_e32 v82, v80
	v_fmamk_f32 v99, v84, 0x3e0293ee, v97
	v_exp_f32_e32 v84, v81
	v_fmamk_f32 v83, v83, 0x3e0293ee, v97
	v_exp_f32_e32 v80, v98
	v_fmamk_f32 v64, v64, 0x3e0293ee, v97
	v_exp_f32_e32 v83, v83
	v_fmamk_f32 v102, v85, 0x3e0293ee, v97
	v_fmamk_f32 v111, v94, 0x3e0293ee, v97
	v_fmamk_f32 v94, v75, 0x3e0293ee, v97
	v_exp_f32_e32 v75, v99
	v_exp_f32_e32 v98, v64
	v_add_f32_e32 v64, 0, v82
	v_fmamk_f32 v103, v86, 0x3e0293ee, v97
	v_exp_f32_e32 v81, v102
	v_add_f32_e32 v64, v84, v64
	v_fmamk_f32 v104, v87, 0x3e0293ee, v97
	v_fmamk_f32 v110, v93, 0x3e0293ee, v97
	v_fmamk_f32 v93, v74, 0x3e0293ee, v97
	v_exp_f32_e32 v74, v103
	v_add_f32_e32 v64, v80, v64
	v_fmamk_f32 v105, v88, 0x3e0293ee, v97
	v_fmamk_f32 v112, v95, 0x3e0293ee, v97
	v_fmamk_f32 v95, v76, 0x3e0293ee, v97
	v_exp_f32_e32 v76, v104
	v_add_f32_e32 v64, v83, v64
	v_fmamk_f32 v106, v89, 0x3e0293ee, v97
	v_fmamk_f32 v107, v90, 0x3e0293ee, v97
	v_fmamk_f32 v90, v71, 0x3e0293ee, v97
	v_exp_f32_e32 v71, v105
	v_add_f32_e32 v64, v75, v64
	v_fmamk_f32 v109, v92, 0x3e0293ee, v97
	v_fmamk_f32 v92, v73, 0x3e0293ee, v97
	v_exp_f32_e32 v73, v106
	v_add_f32_e32 v64, v81, v64
	v_fmamk_f32 v108, v91, 0x3e0293ee, v97
	v_fmamk_f32 v88, v69, 0x3e0293ee, v97
	v_exp_f32_e32 v69, v107
	v_add_f32_e32 v64, v74, v64
	v_fmamk_f32 v91, v72, 0x3e0293ee, v97
	v_exp_f32_e32 v72, v108
	v_add_f32_e32 v64, v76, v64
	v_fmamk_f32 v86, v67, 0x3e0293ee, v97
	v_exp_f32_e32 v67, v109
	v_add_f32_e32 v64, v71, v64
	v_fmamk_f32 v89, v70, 0x3e0293ee, v97
	v_exp_f32_e32 v70, v110
	v_add_f32_e32 v64, v73, v64
	v_fmamk_f32 v85, v66, 0x3e0293ee, v97
	v_exp_f32_e32 v66, v111
	v_add_f32_e32 v64, v69, v64
	v_fmamk_f32 v87, v68, 0x3e0293ee, v97
	v_exp_f32_e32 v68, v112
	v_add_f32_e32 v64, v72, v64
	v_fmamk_f32 v65, v65, 0x3e0293ee, v97
	v_add_f32_e32 v64, v67, v64
	v_exp_f32_e32 v99, v65
	v_add_f32_e32 v64, v70, v64
	v_exp_f32_e32 v85, v85
	v_add_f32_e32 v64, v66, v64
	v_exp_f32_e32 v86, v86
	v_add_f32_e32 v64, v68, v64
	v_exp_f32_e32 v87, v87
	v_add_f32_e32 v64, v98, v64
	v_exp_f32_e32 v88, v88
	v_add_f32_e32 v64, v99, v64
	v_exp_f32_e32 v89, v89
	v_add_f32_e32 v64, v85, v64
	v_exp_f32_e32 v90, v90
	v_add_f32_e32 v64, v86, v64
	v_exp_f32_e32 v91, v91
	v_add_f32_e32 v64, v87, v64
	v_exp_f32_e32 v92, v92
	v_add_f32_e32 v64, v88, v64
	v_exp_f32_e32 v93, v93
	v_add_f32_e32 v64, v89, v64
	v_exp_f32_e32 v94, v94
	v_add_f32_e32 v64, v90, v64
	v_fmamk_f32 v77, v77, 0x3e0293ee, v97
	v_exp_f32_e32 v95, v95
	v_add_f32_e32 v64, v91, v64
	v_fmamk_f32 v78, v78, 0x3e0293ee, v97
	v_exp_f32_e32 v102, v77
	v_add_f32_e32 v64, v92, v64
	v_fmac_f32_e32 v97, 0x3e0293ee, v79
	v_exp_f32_e32 v103, v78
	v_add_f32_e32 v64, v93, v64
	v_exp_f32_e32 v97, v97
	v_add_f32_e32 v64, v94, v64
	v_add_f32_e32 v64, v95, v64
	v_add_f32_e32 v64, v102, v64
	v_add_f32_e32 v64, v103, v64
	v_add_f32_e32 v64, v97, v64
	v_mov_b32_e32 v65, v64
	s_nop 1
	v_permlane32_swap_b32_e32 v64, v65
	v_cvt_pk_bf16_f32 v78, v82, v84
	v_cvt_pk_bf16_f32 v79, v80, v83
	v_cvt_pk_bf16_f32 v80, v75, v81
	v_cvt_pk_bf16_f32 v81, v74, v76
	v_cvt_pk_bf16_f32 v74, v71, v73
	v_cvt_pk_bf16_f32 v75, v69, v72
	v_cvt_pk_bf16_f32 v76, v67, v70
	v_cvt_pk_bf16_f32 v77, v66, v68
	v_cvt_pk_bf16_f32 v66, v98, v99
	v_cvt_pk_bf16_f32 v67, v85, v86
	v_cvt_pk_bf16_f32 v68, v87, v88
	v_cvt_pk_bf16_f32 v69, v89, v90
	v_cvt_pk_bf16_f32 v70, v91, v92
	v_cvt_pk_bf16_f32 v71, v93, v94
	v_cvt_pk_bf16_f32 v72, v95, v102
	v_cvt_pk_bf16_f32 v73, v103, v97
	s_nop 0
	v_permlane32_swap_b32_e32 v78, v80
	v_permlane32_swap_b32_e32 v79, v81
	v_permlane32_swap_b32_e32 v74, v76
	v_permlane32_swap_b32_e32 v75, v77
	v_permlane32_swap_b32_e32 v66, v68
	v_permlane32_swap_b32_e32 v67, v69
	v_permlane32_swap_b32_e32 v70, v72
	v_permlane32_swap_b32_e32 v71, v73
	ds_read_b64_tr_b16 v[82:83], v200 offset:0
	ds_read_b64_tr_b16 v[84:85], v200 offset:0x800
	ds_read_b64_tr_b16 v[86:87], v200 offset:0x1000
	ds_read_b64_tr_b16 v[88:89], v200 offset:0x1800
	ds_read_b64_tr_b16 v[90:91], v200 offset:0x2000
	ds_read_b64_tr_b16 v[92:93], v200 offset:0x2800
	ds_read_b64_tr_b16 v[102:103], v200 offset:0x3000
	ds_read_b64_tr_b16 v[104:105], v200 offset:0x3800
	s_waitcnt lgkmcnt(0)
	s_nop 0
	s_setprio 1
	v_mfma_f32_32x32x16_bf16 v[0:15], v[78:81], v[82:85], v[0:15]
	s_setprio 0
	ds_read_b64_tr_b16 v[82:83], v200 offset:0x200
	ds_read_b64_tr_b16 v[84:85], v200 offset:0xa00
	s_setprio 1
	v_mfma_f32_32x32x16_bf16 v[0:15], v[74:77], v[86:89], v[0:15]
	s_setprio 0
	ds_read_b64_tr_b16 v[86:87], v200 offset:0x1200
	ds_read_b64_tr_b16 v[88:89], v200 offset:0x1a00
	s_setprio 1
	v_mfma_f32_32x32x16_bf16 v[0:15], v[66:69], v[90:93], v[0:15]
	s_setprio 0
	ds_read_b64_tr_b16 v[90:91], v200 offset:0x2200
	ds_read_b64_tr_b16 v[92:93], v200 offset:0x2a00
	ds_read_b64_tr_b16 v[106:107], v200 offset:0x3200
	ds_read_b64_tr_b16 v[108:109], v200 offset:0x3a00
	s_waitcnt lgkmcnt(0)
	s_setprio 1
	v_mfma_f32_32x32x16_bf16 v[0:15], v[70:73], v[102:105], v[0:15]
	v_mfma_f32_32x32x16_bf16 v[48:63], v[78:81], v[82:85], v[48:63]
	s_setprio 0
	ds_read_b64_tr_b16 v[82:83], v200 offset:0x400
	ds_read_b64_tr_b16 v[84:85], v200 offset:0xc00
	s_setprio 1
	v_mfma_f32_32x32x16_bf16 v[48:63], v[74:77], v[86:89], v[48:63]
	s_setprio 0
	ds_read_b64_tr_b16 v[86:87], v200 offset:0x1400
	ds_read_b64_tr_b16 v[88:89], v200 offset:0x1c00
	s_setprio 1
	v_mfma_f32_32x32x16_bf16 v[48:63], v[66:69], v[90:93], v[48:63]
	s_setprio 0
	ds_read_b64_tr_b16 v[90:91], v200 offset:0x2400
	ds_read_b64_tr_b16 v[92:93], v200 offset:0x2c00
	ds_read_b64_tr_b16 v[102:103], v200 offset:0x3400
	ds_read_b64_tr_b16 v[104:105], v200 offset:0x3c00
	s_waitcnt lgkmcnt(0)
	s_setprio 1
	v_mfma_f32_32x32x16_bf16 v[48:63], v[70:73], v[106:109], v[48:63]
	v_mfma_f32_32x32x16_bf16 v[32:47], v[78:81], v[82:85], v[32:47]
	s_setprio 0
	ds_read_b64_tr_b16 v[82:83], v200 offset:0x600
	ds_read_b64_tr_b16 v[84:85], v200 offset:0xe00
	s_setprio 1
	v_mfma_f32_32x32x16_bf16 v[32:47], v[74:77], v[86:89], v[32:47]
	s_setprio 0
	ds_read_b64_tr_b16 v[86:87], v200 offset:0x1600
	ds_read_b64_tr_b16 v[88:89], v200 offset:0x1e00
	s_setprio 1
	v_mfma_f32_32x32x16_bf16 v[32:47], v[66:69], v[90:93], v[32:47]
	s_setprio 0
	ds_read_b64_tr_b16 v[90:91], v200 offset:0x2600
	ds_read_b64_tr_b16 v[92:93], v200 offset:0x2e00
	ds_read_b64_tr_b16 v[106:107], v200 offset:0x3600
	ds_read_b64_tr_b16 v[108:109], v200 offset:0x3e00
	s_waitcnt lgkmcnt(0)
	s_setprio 1
	v_mfma_f32_32x32x16_bf16 v[32:47], v[70:73], v[102:105], v[32:47]
	v_mfma_f32_32x32x16_bf16 v[16:31], v[78:81], v[82:85], v[16:31]
	v_mfma_f32_32x32x16_bf16 v[16:31], v[74:77], v[86:89], v[16:31]
	v_mfma_f32_32x32x16_bf16 v[16:31], v[66:69], v[90:93], v[16:31]
	v_mfma_f32_32x32x16_bf16 v[16:31], v[70:73], v[106:109], v[16:31]
	s_setprio 0
	s_and_saveexec_b64 s[6:7], s[4:5]
	s_cbranch_execz .LBB0_901
; __device__ __forceinline__ void finishSM(f32x16& p0, f32x16& p1, float alpha, float& l_reg, bf16x8& pa0, bf16x8& pa1, bf16x8& pa2, bf16x8& pa3) {
;     ...
;   { auto rr = __builtin_amdgcn_permlane32_swap(__float_as_uint(ps), __float_as_uint(ps), false, false);
;     ps = __uint_as_float(rr[0]) + __uint_as_float(rr[1]); }
;   l_reg = l_reg * alpha + ps;
; template <typename TQ>
; __device__ __forceinline__ void attn_dense_body(const TQ* __restrict__ Qb, const bf16* __restrict__ Kh, const bf16* __restrict__ Vh,
;                                                 unsigned short* __restrict__ Ob, int seq, char* lds, const float* __restrict__ qg, int pos0) {
;     ...
;   if (hi == 0) li_l[r32] = l_reg; asm volatile("s_waitcnt lgkmcnt(0)" ::: "memory");
	v_add_f32_e32 v66, v100, v101
	v_fmac_f32_e32 v66, v199, v161
	v_add_f32_e32 v64, v64, v65
	v_fmac_f32_e32 v64, v66, v96
	ds_write_b32 v198, v64
	s_branch .LBB0_901
